# chainzz3: chain+zigzag with chains ordered srcA-major (same weight fragment for 4 consecutive chains) and operand sharing across the mid-block boundary
# baseline (speedup 1.0000x reference)
; #define PG8_STAGE(bufoff, gbase, voff) do { _Pragma("unroll") for (int _i = 0; _i < 2; ++_i) \
;         __builtin_amdgcn_global_load_lds((const unsigned*)((const char*)(gbase) + (voff)[_i]), (LAS unsigned*)(lds + (bufoff) + ldsw + _i * 8192), 16, 0, 0); } while (0)
; #define PG8_LDA(dst, b, h) do { _Pragma("unroll") for (int m = 0; m < 4; ++m) _Pragma("unroll") for (int k = 0; k < 2; ++k) dst[m][k] = *(const LAS bf16x8*)(lds + PG8_SA(b, h) + aoffk[k] + m * 2048); } while (0)
; #define PG8_LDB(dst, b, h) do { _Pragma("unroll") for (int n = 0; n < 2; ++n) _Pragma("unroll") for (int k = 0; k < 2; ++k) dst[n][k] = *(const LAS bf16x8*)(lds + PG8_SB(b, h) + boffk[k] + n * 2048); } while (0)
; #define PG8_WAIT_V(n) asm volatile("s_waitcnt vmcnt(" #n ")" ::: "memory")
; #define PG8_WAIT_L(n) asm volatile("s_waitcnt lgkmcnt(" #n ")" ::: "memory")
; #define PG8_BAR __builtin_amdgcn_s_barrier()
; #define PG8_SCHED __builtin_amdgcn_sched_barrier(0)
; template <class Epi, class Sched, class GemmT>
; __device__ __forceinline__ void gemm_phase(LAS unsigned char* lds, const GemmT& g, const Sched& S, const Epi& E, const int wid) {
;     ...
;             for (int t = 0; t < nt; t += 2) {
;                 const bool last = (t == nt - 2);
;                 const char* a1 = cA + (size_t)(t + 1) * kstep;
;                 const char* a2 = last ? ns.A : cA + (size_t)(t + 2) * kstep; const char* b2 = last ? ns.B : cB + (size_t)(t + 2) * kstep;
;                 const char* a3 = a2 + kstep; const char* b3 = b2 + kstep;
;                 unsigned vA2[2], vB2[2];
; #pragma unroll
;                 for (int i = 0; i < 2; ++i) { vA2[i] = last ? nvA[i] : voffA[i]; vB2[i] = last ? nvB[i] : voffB[i]; }
;                 const size_t hA2 = last ? nhA : hstepA, hB2 = last ? nhB : hstepB;
;                 PG8_LDB(B0, 0, 0); PG8_LDB(B1, 0, 1); PG8_SCHED; PG8_LDA(At, 0, 0); PG8_STAGE(PG8_SA(1, 1), a1 + hstepA, voffA);
;                 PG8_WAIT_V(8); PG8_WAIT_L(0); PG8_BAR; PG8_MMA(0, 0, At, B0); PG8_MMA(0, 1, At, B1); PG8_BAR; PG8_SCHED;
;                 PG8_LDA(At, 0, 1); PG8_STAGE(PG8_SB(0, 0), b2, vB2); PG8_STAGE(PG8_SB(0, 1), b2 + hB2, vB2); PG8_STAGE(PG8_SA(0, 0), a2, vA2);
;                 PG8_WAIT_V(8); PG8_WAIT_L(0); PG8_BAR; PG8_MMA(1, 0, At, B0); PG8_MMA(1, 1, At, B1); PG8_BAR; PG8_SCHED;
.LBB0_417:
	ds_read_b128 v[140:143], v192
	ds_read_b128 v[144:147], v193
	ds_read_b128 v[148:151], v194
	ds_read_b128 v[152:155], v195
	ds_read_b128 v[156:159], v196
	ds_read_b128 v[160:163], v197
	ds_read_b128 v[164:167], v198
	ds_read_b128 v[168:171], v199
	s_add_u32 s39, s84, 0xfff00080
	s_addc_u32 s40, s85, -1
	s_cmp_eq_u32 s38, 60
	s_cselect_b32 s87, s57, s40
	s_cselect_b32 s86, s56, s39
	s_cselect_b32 s71, s16, s37
	s_cselect_b32 s70, s5, s36
	v_lshl_add_u64 v[176:177], s[84:85], 0, v[128:129]
	s_add_i32 m0, s9, 0xc000
	ds_read_b128 v[172:175], v200
	ds_read_b128 v[208:211], v200 offset:2048
	ds_read_b128 v[212:215], v201
	ds_read_b128 v[216:219], v201 offset:2048
	ds_read_b128 v[220:223], v200 offset:4096
	ds_read_b128 v[224:227], v200 offset:6144
	ds_read_b128 v[230:233], v201 offset:4096
	ds_read_b128 v[234:237], v201 offset:6144
	global_load_lds_dwordx4 v[176:177], off
	v_lshl_add_u64 v[176:177], s[84:85], 0, v[132:133]
	s_add_i32 m0, s9, 0xe000
	s_nop 0
	global_load_lds_dwordx4 v[176:177], off
	s_waitcnt vmcnt(8)
	s_waitcnt lgkmcnt(0)
	s_barrier
	s_setprio 3
	s_waitcnt lgkmcnt(0)
	v_mfma_f32_16x16x32_bf16 v[124:127], v[140:143], v[172:175], v[124:127]
	v_mfma_f32_16x16x32_bf16 v[124:127], v[144:147], v[212:215], v[124:127]
	v_mfma_f32_16x16x32_bf16 v[116:119], v[144:147], v[216:219], v[116:119]
	v_mfma_f32_16x16x32_bf16 v[116:119], v[140:143], v[208:211], v[116:119]
	v_mfma_f32_16x16x32_bf16 v[100:103], v[140:143], v[220:223], v[100:103]
	v_mfma_f32_16x16x32_bf16 v[100:103], v[144:147], v[230:233], v[100:103]
	v_mfma_f32_16x16x32_bf16 v[84:87], v[144:147], v[234:237], v[84:87]
	v_mfma_f32_16x16x32_bf16 v[84:87], v[140:143], v[224:227], v[84:87]
	v_mfma_f32_16x16x32_bf16 v[76:79], v[148:151], v[224:227], v[76:79]
	v_mfma_f32_16x16x32_bf16 v[76:79], v[152:155], v[234:237], v[76:79]
	v_mfma_f32_16x16x32_bf16 v[120:123], v[152:155], v[212:215], v[120:123]
	v_mfma_f32_16x16x32_bf16 v[120:123], v[148:151], v[172:175], v[120:123]
	v_mfma_f32_16x16x32_bf16 v[112:115], v[148:151], v[208:211], v[112:115]
	v_mfma_f32_16x16x32_bf16 v[112:115], v[152:155], v[216:219], v[112:115]
	v_mfma_f32_16x16x32_bf16 v[96:99], v[152:155], v[230:233], v[96:99]
	v_mfma_f32_16x16x32_bf16 v[96:99], v[148:151], v[220:223], v[96:99]
	s_setprio 0
	s_setprio 3
	v_mfma_f32_16x16x32_bf16 v[68:71], v[156:159], v[220:223], v[68:71]
	v_mfma_f32_16x16x32_bf16 v[68:71], v[160:163], v[230:233], v[68:71]
	v_mfma_f32_16x16x32_bf16 v[108:111], v[160:163], v[212:215], v[108:111]
	v_mfma_f32_16x16x32_bf16 v[108:111], v[156:159], v[172:175], v[108:111]
	v_mfma_f32_16x16x32_bf16 v[92:95], v[156:159], v[208:211], v[92:95]
	v_mfma_f32_16x16x32_bf16 v[92:95], v[160:163], v[216:219], v[92:95]
	v_mfma_f32_16x16x32_bf16 v[48:51], v[160:163], v[234:237], v[48:51]
	v_mfma_f32_16x16x32_bf16 v[48:51], v[156:159], v[224:227], v[48:51]
	v_mfma_f32_16x16x32_bf16 v[40:43], v[164:167], v[224:227], v[40:43]
	v_mfma_f32_16x16x32_bf16 v[40:43], v[168:171], v[234:237], v[40:43]
	v_mfma_f32_16x16x32_bf16 v[104:107], v[168:171], v[212:215], v[104:107]
	v_mfma_f32_16x16x32_bf16 v[104:107], v[164:167], v[172:175], v[104:107]
	v_mfma_f32_16x16x32_bf16 v[88:91], v[164:167], v[208:211], v[88:91]
	v_mfma_f32_16x16x32_bf16 v[88:91], v[168:171], v[216:219], v[88:91]
	v_mfma_f32_16x16x32_bf16 v[64:67], v[168:171], v[230:233], v[64:67]
	v_mfma_f32_16x16x32_bf16 v[64:67], v[164:167], v[220:223], v[64:67]
	s_setprio 0
	s_barrier
	s_add_i32 s39, s35, s68
	v_lshl_add_u64 v[176:177], s[70:71], 0, v[130:131]
	s_mov_b32 m0, s39
	ds_read_b128 v[172:175], v200 offset:16384
	ds_read_b128 v[208:211], v200 offset:18432
	ds_read_b128 v[212:215], v201 offset:16384
	ds_read_b128 v[216:219], v201 offset:18432
	ds_read_b128 v[220:223], v200 offset:20480
	ds_read_b128 v[224:227], v200 offset:22528
	ds_read_b128 v[230:233], v201 offset:20480
	ds_read_b128 v[234:237], v201 offset:22528
	global_load_lds_dwordx4 v[176:177], off
	s_add_i32 m0, s39, 0x2000
	s_add_u32 s40, s70, 0x100000
	v_lshl_add_u64 v[180:181], s[70:71], 0, v[134:135]
	s_addc_u32 s41, s71, 0
	s_add_i32 s39, s69, s68
	global_load_lds_dwordx4 v[180:181], off
	v_lshl_add_u64 v[184:185], s[40:41], 0, v[130:131]
	s_mov_b32 m0, s39
	v_lshl_add_u64 v[188:189], s[86:87], 0, v[132:133]
	global_load_lds_dwordx4 v[184:185], off
	v_lshl_add_u64 v[184:185], s[40:41], 0, v[134:135]
	s_add_i32 m0, s39, 0x2000
	s_nop 0
	global_load_lds_dwordx4 v[184:185], off
	v_lshl_add_u64 v[184:185], s[86:87], 0, v[128:129]
	s_mov_b32 m0, s9
	s_nop 0
	global_load_lds_dwordx4 v[184:185], off
	s_mov_b32 m0, s29
	s_nop 0
	global_load_lds_dwordx4 v[188:189], off
	s_waitcnt vmcnt(8)
	s_waitcnt lgkmcnt(0)
	s_barrier
; #define PG8_STAGE(bufoff, gbase, voff) do { _Pragma("unroll") for (int _i = 0; _i < 2; ++_i) \
;         __builtin_amdgcn_global_load_lds((const unsigned*)((const char*)(gbase) + (voff)[_i]), (LAS unsigned*)(lds + (bufoff) + ldsw + _i * 8192), 16, 0, 0); } while (0)
; #define PG8_LDA(dst, b, h) do { _Pragma("unroll") for (int m = 0; m < 4; ++m) _Pragma("unroll") for (int k = 0; k < 2; ++k) dst[m][k] = *(const LAS bf16x8*)(lds + PG8_SA(b, h) + aoffk[k] + m * 2048); } while (0)
; #define PG8_LDB(dst, b, h) do { _Pragma("unroll") for (int n = 0; n < 2; ++n) _Pragma("unroll") for (int k = 0; k < 2; ++k) dst[n][k] = *(const LAS bf16x8*)(lds + PG8_SB(b, h) + boffk[k] + n * 2048); } while (0)
; #define PG8_WAIT_V(n) asm volatile("s_waitcnt vmcnt(" #n ")" ::: "memory")
; #define PG8_WAIT_L(n) asm volatile("s_waitcnt lgkmcnt(" #n ")" ::: "memory")
; #define PG8_BAR __builtin_amdgcn_s_barrier()
; #define PG8_SCHED __builtin_amdgcn_sched_barrier(0)
; template <class Epi, class Sched, class GemmT>
; __device__ __forceinline__ void gemm_phase(LAS unsigned char* lds, const GemmT& g, const Sched& S, const Epi& E, const int wid) {
;     ...
;                 PG8_WAIT_V(8); PG8_WAIT_L(0); PG8_BAR; PG8_MMA(1, 0, At, B0); PG8_MMA(1, 1, At, B1); PG8_BAR; PG8_SCHED;
;                 PG8_LDB(B0, 1, 0); PG8_LDB(B1, 1, 1); PG8_SCHED; PG8_LDA(At, 1, 0); PG8_STAGE(PG8_SA(0, 1), a2 + hA2, vA2);
;                 PG8_WAIT_V(8); PG8_WAIT_L(0); PG8_BAR; PG8_MMA(0, 0, At, B0); PG8_MMA(0, 1, At, B1); PG8_BAR; PG8_SCHED;
	s_setprio 3
	s_waitcnt lgkmcnt(0)
	v_mfma_f32_16x16x32_bf16 v[12:15], v[140:143], v[220:223], v[12:15]
	v_mfma_f32_16x16x32_bf16 v[12:15], v[144:147], v[230:233], v[12:15]
	v_mfma_f32_16x16x32_bf16 v[28:31], v[144:147], v[212:215], v[28:31]
	v_mfma_f32_16x16x32_bf16 v[28:31], v[140:143], v[172:175], v[28:31]
	v_mfma_f32_16x16x32_bf16 v[20:23], v[140:143], v[208:211], v[20:23]
	v_mfma_f32_16x16x32_bf16 v[20:23], v[144:147], v[216:219], v[20:23]
	v_mfma_f32_16x16x32_bf16 v[4:7], v[144:147], v[234:237], v[4:7]
	v_mfma_f32_16x16x32_bf16 v[4:7], v[140:143], v[224:227], v[4:7]
	v_mfma_f32_16x16x32_bf16 v[0:3], v[148:151], v[224:227], v[0:3]
	v_mfma_f32_16x16x32_bf16 v[0:3], v[152:155], v[234:237], v[0:3]
	v_mfma_f32_16x16x32_bf16 v[24:27], v[152:155], v[212:215], v[24:27]
	v_mfma_f32_16x16x32_bf16 v[24:27], v[148:151], v[172:175], v[24:27]
	v_mfma_f32_16x16x32_bf16 v[16:19], v[148:151], v[208:211], v[16:19]
	v_mfma_f32_16x16x32_bf16 v[16:19], v[152:155], v[216:219], v[16:19]
	v_mfma_f32_16x16x32_bf16 v[8:11], v[152:155], v[230:233], v[8:11]
	v_mfma_f32_16x16x32_bf16 v[8:11], v[148:151], v[220:223], v[8:11]
	s_setprio 0
	s_setprio 3
	v_mfma_f32_16x16x32_bf16 v[52:55], v[156:159], v[220:223], v[52:55]
	v_mfma_f32_16x16x32_bf16 v[52:55], v[160:163], v[230:233], v[52:55]
	v_mfma_f32_16x16x32_bf16 v[80:83], v[160:163], v[212:215], v[80:83]
	v_mfma_f32_16x16x32_bf16 v[80:83], v[156:159], v[172:175], v[80:83]
	v_mfma_f32_16x16x32_bf16 v[60:63], v[156:159], v[208:211], v[60:63]
	v_mfma_f32_16x16x32_bf16 v[60:63], v[160:163], v[216:219], v[60:63]
	v_mfma_f32_16x16x32_bf16 v[36:39], v[160:163], v[234:237], v[36:39]
	v_mfma_f32_16x16x32_bf16 v[36:39], v[156:159], v[224:227], v[36:39]
	v_mfma_f32_16x16x32_bf16 v[32:35], v[164:167], v[224:227], v[32:35]
	v_mfma_f32_16x16x32_bf16 v[32:35], v[168:171], v[234:237], v[32:35]
	v_mfma_f32_16x16x32_bf16 v[72:75], v[168:171], v[212:215], v[72:75]
	v_mfma_f32_16x16x32_bf16 v[72:75], v[164:167], v[172:175], v[72:75]
	v_mfma_f32_16x16x32_bf16 v[56:59], v[164:167], v[208:211], v[56:59]
	v_mfma_f32_16x16x32_bf16 v[56:59], v[168:171], v[216:219], v[56:59]
	v_mfma_f32_16x16x32_bf16 v[44:47], v[168:171], v[230:233], v[44:47]
	v_mfma_f32_16x16x32_bf16 v[44:47], v[164:167], v[220:223], v[44:47]
	s_setprio 0
	s_barrier
	s_add_i32 s39, 0, 0x18000
	s_add_i32 s48, 0, 0x1c000
	v_add_u32_e32 v140, s39, v187
	v_add_u32_e32 v144, s39, v190
	v_add_u32_e32 v156, s48, v187
	v_add_u32_e32 v160, s48, v190
	ds_read_b128 v[140:143], v140
	ds_read_b128 v[144:147], v144
	ds_read_b128 v[148:151], v202
	ds_read_b128 v[152:155], v203
	ds_read_b128 v[156:159], v156
	ds_read_b128 v[160:163], v160
	ds_read_b128 v[164:167], v204
	ds_read_b128 v[168:171], v205
	s_add_u32 s40, s86, 0x100000
	s_addc_u32 s41, s87, 0
	s_mov_b32 m0, s93
	v_lshl_add_u64 v[238:239], s[40:41], 0, v[128:129]
	ds_read_b128 v[172:175], v200 offset:32768
	ds_read_b128 v[208:211], v200 offset:34816
	ds_read_b128 v[212:215], v201 offset:32768
	ds_read_b128 v[216:219], v201 offset:34816
	ds_read_b128 v[220:223], v200 offset:36864
	ds_read_b128 v[224:227], v200 offset:38912
	ds_read_b128 v[230:233], v201 offset:36864
	ds_read_b128 v[234:237], v201 offset:38912
	global_load_lds_dwordx4 v[238:239], off
	v_lshl_add_u64 v[238:239], s[40:41], 0, v[132:133]
	s_mov_b32 m0, s6
	s_nop 0
	global_load_lds_dwordx4 v[238:239], off
	s_waitcnt vmcnt(8)
	s_waitcnt lgkmcnt(0)
	s_barrier
	s_setprio 3
	s_waitcnt lgkmcnt(0)
	v_mfma_f32_16x16x32_bf16 v[100:103], v[140:143], v[220:223], v[100:103]
	v_mfma_f32_16x16x32_bf16 v[100:103], v[144:147], v[230:233], v[100:103]
	v_mfma_f32_16x16x32_bf16 v[124:127], v[144:147], v[212:215], v[124:127]
	v_mfma_f32_16x16x32_bf16 v[124:127], v[140:143], v[172:175], v[124:127]
	v_mfma_f32_16x16x32_bf16 v[116:119], v[140:143], v[208:211], v[116:119]
	v_mfma_f32_16x16x32_bf16 v[116:119], v[144:147], v[216:219], v[116:119]
	v_mfma_f32_16x16x32_bf16 v[84:87], v[144:147], v[234:237], v[84:87]
	v_mfma_f32_16x16x32_bf16 v[84:87], v[140:143], v[224:227], v[84:87]
	v_mfma_f32_16x16x32_bf16 v[76:79], v[148:151], v[224:227], v[76:79]
	v_mfma_f32_16x16x32_bf16 v[76:79], v[152:155], v[234:237], v[76:79]
	v_mfma_f32_16x16x32_bf16 v[120:123], v[152:155], v[212:215], v[120:123]
	v_mfma_f32_16x16x32_bf16 v[120:123], v[148:151], v[172:175], v[120:123]
	v_mfma_f32_16x16x32_bf16 v[112:115], v[148:151], v[208:211], v[112:115]
	v_mfma_f32_16x16x32_bf16 v[112:115], v[152:155], v[216:219], v[112:115]
	v_mfma_f32_16x16x32_bf16 v[96:99], v[152:155], v[230:233], v[96:99]
	v_mfma_f32_16x16x32_bf16 v[96:99], v[148:151], v[220:223], v[96:99]
	s_setprio 0
	s_setprio 3
	v_mfma_f32_16x16x32_bf16 v[68:71], v[156:159], v[220:223], v[68:71]
	v_mfma_f32_16x16x32_bf16 v[68:71], v[160:163], v[230:233], v[68:71]
	v_mfma_f32_16x16x32_bf16 v[108:111], v[160:163], v[212:215], v[108:111]
	v_mfma_f32_16x16x32_bf16 v[108:111], v[156:159], v[172:175], v[108:111]
	v_mfma_f32_16x16x32_bf16 v[92:95], v[156:159], v[208:211], v[92:95]
	v_mfma_f32_16x16x32_bf16 v[92:95], v[160:163], v[216:219], v[92:95]
	v_mfma_f32_16x16x32_bf16 v[48:51], v[160:163], v[234:237], v[48:51]
	v_mfma_f32_16x16x32_bf16 v[48:51], v[156:159], v[224:227], v[48:51]
	v_mfma_f32_16x16x32_bf16 v[40:43], v[164:167], v[224:227], v[40:43]
	v_mfma_f32_16x16x32_bf16 v[40:43], v[168:171], v[234:237], v[40:43]
	v_mfma_f32_16x16x32_bf16 v[104:107], v[168:171], v[212:215], v[104:107]
	v_mfma_f32_16x16x32_bf16 v[104:107], v[164:167], v[172:175], v[104:107]
	v_mfma_f32_16x16x32_bf16 v[88:91], v[164:167], v[208:211], v[88:91]
	v_mfma_f32_16x16x32_bf16 v[88:91], v[168:171], v[216:219], v[88:91]
	v_mfma_f32_16x16x32_bf16 v[64:67], v[168:171], v[230:233], v[64:67]
	v_mfma_f32_16x16x32_bf16 v[64:67], v[164:167], v[220:223], v[64:67]
	s_setprio 0
	s_barrier
; #define PG8_STAGE(bufoff, gbase, voff) do { _Pragma("unroll") for (int _i = 0; _i < 2; ++_i) \
;         __builtin_amdgcn_global_load_lds((const unsigned*)((const char*)(gbase) + (voff)[_i]), (LAS unsigned*)(lds + (bufoff) + ldsw + _i * 8192), 16, 0, 0); } while (0)
; #define PG8_LDA(dst, b, h) do { _Pragma("unroll") for (int m = 0; m < 4; ++m) _Pragma("unroll") for (int k = 0; k < 2; ++k) dst[m][k] = *(const LAS bf16x8*)(lds + PG8_SA(b, h) + aoffk[k] + m * 2048); } while (0)
; #define PG8_WAIT_V(n) asm volatile("s_waitcnt vmcnt(" #n ")" ::: "memory")
; #define PG8_WAIT_L(n) asm volatile("s_waitcnt lgkmcnt(" #n ")" ::: "memory")
; #define PG8_BAR __builtin_amdgcn_s_barrier()
; #define PG8_SCHED __builtin_amdgcn_sched_barrier(0)
; template <class Epi, class Sched, class GemmT>
; __device__ __forceinline__ void gemm_phase(LAS unsigned char* lds, const GemmT& g, const Sched& S, const Epi& E, const int wid) {
;     ...
;                 PG8_LDA(At, 1, 1); PG8_STAGE(PG8_SB(1, 0), b3, vB2); PG8_STAGE(PG8_SB(1, 1), b3 + hB2, vB2); PG8_STAGE(PG8_SA(1, 0), a3, vA2);
;                 PG8_WAIT_V(8); PG8_WAIT_L(0); PG8_BAR; PG8_MMA(1, 0, At, B0); PG8_MMA(1, 1, At, B1); PG8_BAR; PG8_SCHED;
;             }
;             if constexpr (NSEG > 1) { if (sgi + 1 < NSEG) E.mid(acc, cur, sgi, wr, wc, fr, fq); }
;             cs = ns; cA = ns.A; cB = ns.B; hstepA = nhA; hstepB = nhB;
; #pragma unroll
;             for (int i = 0; i < 2; ++i) { voffA[i] = nvA[i]; voffB[i] = nvB[i]; }
;         }
;         if (wr == 0) PG8_BAR;
	s_add_i32 s39, s39, s68
	v_lshl_add_u64 v[176:177], v[176:177], 0, s[66:67]
	s_mov_b32 m0, s39
	ds_read_b128 v[172:175], v200 offset:49152
	ds_read_b128 v[208:211], v200 offset:51200
	ds_read_b128 v[212:215], v201 offset:49152
	ds_read_b128 v[216:219], v201 offset:51200
	ds_read_b128 v[220:223], v200 offset:53248
	ds_read_b128 v[224:227], v200 offset:55296
	ds_read_b128 v[230:233], v201 offset:53248
	ds_read_b128 v[234:237], v201 offset:55296
	global_load_lds_dwordx4 v[176:177], off
	s_add_i32 m0, s39, 0x2000
	s_add_u32 s40, s70, 0x100080
	v_lshl_add_u64 v[176:177], v[180:181], 0, s[66:67]
	s_addc_u32 s41, s71, 0
	s_add_i32 s39, s48, s68
	global_load_lds_dwordx4 v[176:177], off
	v_lshl_add_u64 v[176:177], s[40:41], 0, v[130:131]
	s_mov_b32 m0, s39
	s_nop 0
	global_load_lds_dwordx4 v[176:177], off
	v_lshl_add_u64 v[176:177], s[40:41], 0, v[134:135]
	s_add_i32 m0, s39, 0x2000
	s_nop 0
	global_load_lds_dwordx4 v[176:177], off
	v_lshl_add_u64 v[176:177], v[184:185], 0, s[66:67]
	s_mov_b32 m0, s7
	s_nop 0
	global_load_lds_dwordx4 v[176:177], off
	v_lshl_add_u64 v[176:177], v[188:189], 0, s[66:67]
	s_mov_b32 m0, s12
	s_nop 0
	global_load_lds_dwordx4 v[176:177], off
	s_waitcnt vmcnt(8)
	s_waitcnt lgkmcnt(0)
	s_barrier
	s_setprio 3
	s_waitcnt lgkmcnt(0)
	v_mfma_f32_16x16x32_bf16 v[12:15], v[140:143], v[220:223], v[12:15]
	v_mfma_f32_16x16x32_bf16 v[12:15], v[144:147], v[230:233], v[12:15]
	v_mfma_f32_16x16x32_bf16 v[28:31], v[144:147], v[212:215], v[28:31]
	v_mfma_f32_16x16x32_bf16 v[28:31], v[140:143], v[172:175], v[28:31]
	v_mfma_f32_16x16x32_bf16 v[20:23], v[140:143], v[208:211], v[20:23]
	v_mfma_f32_16x16x32_bf16 v[20:23], v[144:147], v[216:219], v[20:23]
	v_mfma_f32_16x16x32_bf16 v[4:7], v[144:147], v[234:237], v[4:7]
	v_mfma_f32_16x16x32_bf16 v[4:7], v[140:143], v[224:227], v[4:7]
	v_mfma_f32_16x16x32_bf16 v[0:3], v[148:151], v[224:227], v[0:3]
	v_mfma_f32_16x16x32_bf16 v[0:3], v[152:155], v[234:237], v[0:3]
	v_mfma_f32_16x16x32_bf16 v[24:27], v[152:155], v[212:215], v[24:27]
	v_mfma_f32_16x16x32_bf16 v[24:27], v[148:151], v[172:175], v[24:27]
	v_mfma_f32_16x16x32_bf16 v[16:19], v[148:151], v[208:211], v[16:19]
	v_mfma_f32_16x16x32_bf16 v[16:19], v[152:155], v[216:219], v[16:19]
	v_mfma_f32_16x16x32_bf16 v[8:11], v[152:155], v[230:233], v[8:11]
	v_mfma_f32_16x16x32_bf16 v[8:11], v[148:151], v[220:223], v[8:11]
	s_setprio 0
	s_setprio 3
	v_mfma_f32_16x16x32_bf16 v[52:55], v[156:159], v[220:223], v[52:55]
	v_mfma_f32_16x16x32_bf16 v[52:55], v[160:163], v[230:233], v[52:55]
	v_mfma_f32_16x16x32_bf16 v[80:83], v[160:163], v[212:215], v[80:83]
	v_mfma_f32_16x16x32_bf16 v[80:83], v[156:159], v[172:175], v[80:83]
	v_mfma_f32_16x16x32_bf16 v[60:63], v[156:159], v[208:211], v[60:63]
	v_mfma_f32_16x16x32_bf16 v[60:63], v[160:163], v[216:219], v[60:63]
	v_mfma_f32_16x16x32_bf16 v[36:39], v[160:163], v[234:237], v[36:39]
	v_mfma_f32_16x16x32_bf16 v[36:39], v[156:159], v[224:227], v[36:39]
	v_mfma_f32_16x16x32_bf16 v[32:35], v[164:167], v[224:227], v[32:35]
	v_mfma_f32_16x16x32_bf16 v[32:35], v[168:171], v[234:237], v[32:35]
	v_mfma_f32_16x16x32_bf16 v[72:75], v[168:171], v[212:215], v[72:75]
	v_mfma_f32_16x16x32_bf16 v[72:75], v[164:167], v[172:175], v[72:75]
	v_mfma_f32_16x16x32_bf16 v[56:59], v[164:167], v[208:211], v[56:59]
	v_mfma_f32_16x16x32_bf16 v[56:59], v[168:171], v[216:219], v[56:59]
	v_mfma_f32_16x16x32_bf16 v[44:47], v[168:171], v[230:233], v[44:47]
	v_mfma_f32_16x16x32_bf16 v[44:47], v[164:167], v[220:223], v[44:47]
	s_setprio 0
	s_barrier
	s_add_i32 s38, s38, 2
	s_add_u32 s84, s84, 0x100
	s_addc_u32 s85, s85, 0
	s_add_u32 s36, s36, 0x100
	s_addc_u32 s37, s37, 0
	s_cmp_gt_u32 s38, 61
	s_cbranch_scc0 .LBB0_417
	s_and_b64 vcc, exec, s[20:21]
	s_cbranch_vccz .LBB0_420
	s_barrier

; #define PG8_STAGE(bufoff, gbase, voff) do { _Pragma("unroll") for (int _i = 0; _i < 2; ++_i) \
;         __builtin_amdgcn_global_load_lds((const unsigned*)((const char*)(gbase) + (voff)[_i]), (LAS unsigned*)(lds + (bufoff) + ldsw + _i * 8192), 16, 0, 0); } while (0)
; #define PG8_LDA(dst, b, h) do { _Pragma("unroll") for (int m = 0; m < 4; ++m) _Pragma("unroll") for (int k = 0; k < 2; ++k) dst[m][k] = *(const LAS bf16x8*)(lds + PG8_SA(b, h) + aoffk[k] + m * 2048); } while (0)
; #define PG8_LDB(dst, b, h) do { _Pragma("unroll") for (int n = 0; n < 2; ++n) _Pragma("unroll") for (int k = 0; k < 2; ++k) dst[n][k] = *(const LAS bf16x8*)(lds + PG8_SB(b, h) + boffk[k] + n * 2048); } while (0)
; #define PG8_WAIT_V(n) asm volatile("s_waitcnt vmcnt(" #n ")" ::: "memory")
; #define PG8_WAIT_L(n) asm volatile("s_waitcnt lgkmcnt(" #n ")" ::: "memory")
; #define PG8_BAR __builtin_amdgcn_s_barrier()
; #define PG8_SCHED __builtin_amdgcn_sched_barrier(0)
; template <class Epi, class Sched, class GemmT>
; __device__ __forceinline__ void gemm_phase(LAS unsigned char* lds, const GemmT& g, const Sched& S, const Epi& E, const int wid) {
;     ...
;             for (int t = 0; t < nt; t += 2) {
;                 const bool last = (t == nt - 2);
;                 const char* a1 = cA + (size_t)(t + 1) * kstep;
;                 const char* a2 = last ? ns.A : cA + (size_t)(t + 2) * kstep; const char* b2 = last ? ns.B : cB + (size_t)(t + 2) * kstep;
;                 const char* a3 = a2 + kstep; const char* b3 = b2 + kstep;
;                 unsigned vA2[2], vB2[2];
; #pragma unroll
;                 for (int i = 0; i < 2; ++i) { vA2[i] = last ? nvA[i] : voffA[i]; vB2[i] = last ? nvB[i] : voffB[i]; }
;                 const size_t hA2 = last ? nhA : hstepA, hB2 = last ? nhB : hstepB;
;                 PG8_LDB(B0, 0, 0); PG8_LDB(B1, 0, 1); PG8_SCHED; PG8_LDA(At, 0, 0); PG8_STAGE(PG8_SA(1, 1), a1 + hstepA, voffA);
;                 PG8_WAIT_V(8); PG8_WAIT_L(0); PG8_BAR; PG8_MMA(0, 0, At, B0); PG8_MMA(0, 1, At, B1); PG8_BAR; PG8_SCHED;
;                 PG8_LDA(At, 0, 1); PG8_STAGE(PG8_SB(0, 0), b2, vB2); PG8_STAGE(PG8_SB(0, 1), b2 + hB2, vB2); PG8_STAGE(PG8_SA(0, 0), a2, vA2);
;                 PG8_WAIT_V(8); PG8_WAIT_L(0); PG8_BAR; PG8_MMA(1, 0, At, B0); PG8_MMA(1, 1, At, B1); PG8_BAR; PG8_SCHED;
.LBB0_764:
	s_cmp_eq_u32 s43, s56
	s_cselect_b64 vcc, -1, 0
	s_add_i32 s90, s90, 2
	v_add_u32_e32 v131, s62, v208
	s_add_u32 s48, s50, s56
	v_add_u32_e32 v133, s62, v209
	ds_read_b128 v[144:147], v131
	ds_read_b128 v[148:151], v133
	v_add_u32_e32 v131, s63, v208
	s_addc_u32 s49, s51, s57
	v_add_u32_e32 v133, s63, v209
	ds_read_b128 v[152:155], v131
	ds_read_b128 v[156:159], v133
	v_add_u32_e32 v131, s64, v208
	s_add_u32 s58, s48, 0x100
	v_add_u32_e32 v133, s64, v209
	ds_read_b128 v[160:163], v131
	ds_read_b128 v[164:167], v133
	v_add_u32_e32 v131, s65, v208
	s_addc_u32 s59, s49, 0
	v_add_u32_e32 v133, s65, v209
	ds_read_b128 v[168:171], v131
	ds_read_b128 v[172:175], v133
	s_and_b64 s[48:49], vcc, exec
	s_cselect_b32 s59, s19, s59
	s_cselect_b32 s58, s18, s58
	s_add_u32 s60, s85, s56
	s_addc_u32 s61, s89, s57
	s_and_b64 s[48:49], vcc, exec
	v_cndmask_b32_e32 v138, v132, v190, vcc
	v_cndmask_b32_e32 v0, v143, v214, vcc
	v_cndmask_b32_e32 v140, v130, v194, vcc
	v_cndmask_b32_e32 v188, v142, v192, vcc
	s_cselect_b32 s61, s13, s61
	s_cselect_b32 s60, s12, s60
	s_cselect_b32 s91, 0, s45
	s_cselect_b32 s92, s6, s44
	v_lshl_add_u64 v[202:203], v[134:135], 0, s[56:57]
	s_add_i32 m0, s14, 0xc000
	ds_read_b128 v[176:179], v212
	ds_read_b128 v[180:183], v212 offset:2048
	ds_read_b128 v[184:187], v213
	ds_read_b128 v[216:219], v213 offset:2048
	ds_read_b128 v[220:223], v212 offset:4096
	ds_read_b128 v[224:227], v212 offset:6144
	ds_read_b128 v[230:233], v213 offset:4096
	ds_read_b128 v[234:237], v213 offset:6144
	global_load_lds_dwordx4 v[202:203], off
	v_lshl_add_u64 v[202:203], v[136:137], 0, s[56:57]
	s_add_i32 m0, s14, 0xe000
	s_nop 0
	global_load_lds_dwordx4 v[202:203], off
	s_waitcnt vmcnt(8)
	s_waitcnt lgkmcnt(0)
	s_barrier
	s_setprio 3
	s_waitcnt lgkmcnt(0)
	v_mfma_f32_16x16x32_bf16 v[94:97], v[144:147], v[220:223], v[94:97]
	v_mfma_f32_16x16x32_bf16 v[94:97], v[148:151], v[230:233], v[94:97]
	v_mfma_f32_16x16x32_bf16 v[126:129], v[148:151], v[184:187], v[126:129]
	v_mfma_f32_16x16x32_bf16 v[126:129], v[144:147], v[176:179], v[126:129]
	v_mfma_f32_16x16x32_bf16 v[110:113], v[144:147], v[180:183], v[110:113]
	v_mfma_f32_16x16x32_bf16 v[110:113], v[148:151], v[216:219], v[110:113]
	v_mfma_f32_16x16x32_bf16 v[78:81], v[148:151], v[234:237], v[78:81]
	v_mfma_f32_16x16x32_bf16 v[78:81], v[144:147], v[224:227], v[78:81]
	v_mfma_f32_16x16x32_bf16 v[74:77], v[152:155], v[224:227], v[74:77]
	v_mfma_f32_16x16x32_bf16 v[74:77], v[156:159], v[234:237], v[74:77]
	v_mfma_f32_16x16x32_bf16 v[122:125], v[156:159], v[184:187], v[122:125]
	v_mfma_f32_16x16x32_bf16 v[122:125], v[152:155], v[176:179], v[122:125]
	v_mfma_f32_16x16x32_bf16 v[106:109], v[152:155], v[180:183], v[106:109]
	v_mfma_f32_16x16x32_bf16 v[106:109], v[156:159], v[216:219], v[106:109]
	v_mfma_f32_16x16x32_bf16 v[90:93], v[156:159], v[230:233], v[90:93]
	v_mfma_f32_16x16x32_bf16 v[90:93], v[152:155], v[220:223], v[90:93]
	s_setprio 0
	s_setprio 3
	v_mfma_f32_16x16x32_bf16 v[86:89], v[160:163], v[220:223], v[86:89]
	v_mfma_f32_16x16x32_bf16 v[86:89], v[164:167], v[230:233], v[86:89]
	v_mfma_f32_16x16x32_bf16 v[118:121], v[164:167], v[184:187], v[118:121]
	v_mfma_f32_16x16x32_bf16 v[118:121], v[160:163], v[176:179], v[118:121]
	v_mfma_f32_16x16x32_bf16 v[102:105], v[160:163], v[180:183], v[102:105]
	v_mfma_f32_16x16x32_bf16 v[102:105], v[164:167], v[216:219], v[102:105]
	v_mfma_f32_16x16x32_bf16 v[70:73], v[164:167], v[234:237], v[70:73]
	v_mfma_f32_16x16x32_bf16 v[70:73], v[160:163], v[224:227], v[70:73]
	v_mfma_f32_16x16x32_bf16 v[66:69], v[168:171], v[224:227], v[66:69]
	v_mfma_f32_16x16x32_bf16 v[66:69], v[172:175], v[234:237], v[66:69]
	v_mfma_f32_16x16x32_bf16 v[114:117], v[172:175], v[184:187], v[114:117]
	v_mfma_f32_16x16x32_bf16 v[114:117], v[168:171], v[176:179], v[114:117]
	v_mfma_f32_16x16x32_bf16 v[98:101], v[168:171], v[180:183], v[98:101]
	v_mfma_f32_16x16x32_bf16 v[98:101], v[172:175], v[216:219], v[98:101]
	v_mfma_f32_16x16x32_bf16 v[82:85], v[172:175], v[230:233], v[82:85]
	v_mfma_f32_16x16x32_bf16 v[82:85], v[168:171], v[220:223], v[82:85]
	s_setprio 0
	s_barrier
	s_add_i32 s48, s62, s68
	s_mov_b32 m0, s48
	ds_read_b128 v[176:179], v212 offset:16384
	ds_read_b128 v[180:183], v213 offset:16384
	ds_read_b128 v[184:187], v212 offset:18432
	ds_read_b128 v[216:219], v213 offset:18432
	ds_read_b128 v[220:223], v212 offset:20480
	ds_read_b128 v[224:227], v213 offset:20480
	ds_read_b128 v[230:233], v212 offset:22528
	ds_read_b128 v[234:237], v213 offset:22528
	global_load_lds_dwordx4 v0, s[60:61]
	s_add_i32 m0, s48, 0x2000
	v_mov_b32_e32 v189, v1
	s_add_u32 s48, s60, s92
	v_lshl_add_u64 v[202:203], s[60:61], 0, v[0:1]
	v_lshl_add_u64 v[238:239], s[60:61], 0, v[188:189]
	global_load_lds_dwordx4 v188, s[60:61]
	s_addc_u32 s49, s61, s91
	s_add_i32 s60, s64, s68
	s_mov_b32 m0, s60
	v_mov_b32_e32 v139, v1
	global_load_lds_dwordx4 v0, s[48:49]
	s_add_i32 m0, s60, 0x2000
	v_mov_b32_e32 v141, v1
	global_load_lds_dwordx4 v188, s[48:49]
	s_mov_b32 m0, s14
	v_lshl_add_u64 v[240:241], s[48:49], 0, v[0:1]
	global_load_lds_dwordx4 v138, s[58:59]
	s_mov_b32 m0, s15
	v_lshl_add_u64 v[242:243], s[48:49], 0, v[188:189]
	global_load_lds_dwordx4 v140, s[58:59]
	s_waitcnt vmcnt(8)
	s_waitcnt lgkmcnt(0)
	v_lshl_add_u64 v[188:189], s[58:59], 0, v[138:139]
	v_lshl_add_u64 v[244:245], s[58:59], 0, v[140:141]
	s_barrier
; #define PG8_STAGE(bufoff, gbase, voff) do { _Pragma("unroll") for (int _i = 0; _i < 2; ++_i) \
;         __builtin_amdgcn_global_load_lds((const unsigned*)((const char*)(gbase) + (voff)[_i]), (LAS unsigned*)(lds + (bufoff) + ldsw + _i * 8192), 16, 0, 0); } while (0)
; #define PG8_LDA(dst, b, h) do { _Pragma("unroll") for (int m = 0; m < 4; ++m) _Pragma("unroll") for (int k = 0; k < 2; ++k) dst[m][k] = *(const LAS bf16x8*)(lds + PG8_SA(b, h) + aoffk[k] + m * 2048); } while (0)
; #define PG8_LDB(dst, b, h) do { _Pragma("unroll") for (int n = 0; n < 2; ++n) _Pragma("unroll") for (int k = 0; k < 2; ++k) dst[n][k] = *(const LAS bf16x8*)(lds + PG8_SB(b, h) + boffk[k] + n * 2048); } while (0)
; #define PG8_WAIT_V(n) asm volatile("s_waitcnt vmcnt(" #n ")" ::: "memory")
; #define PG8_WAIT_L(n) asm volatile("s_waitcnt lgkmcnt(" #n ")" ::: "memory")
; #define PG8_BAR __builtin_amdgcn_s_barrier()
; #define PG8_SCHED __builtin_amdgcn_sched_barrier(0)
; template <class Epi, class Sched, class GemmT>
; __device__ __forceinline__ void gemm_phase(LAS unsigned char* lds, const GemmT& g, const Sched& S, const Epi& E, const int wid) {
;     ...
;                 PG8_WAIT_V(8); PG8_WAIT_L(0); PG8_BAR; PG8_MMA(1, 0, At, B0); PG8_MMA(1, 1, At, B1); PG8_BAR; PG8_SCHED;
;                 PG8_LDB(B0, 1, 0); PG8_LDB(B1, 1, 1); PG8_SCHED; PG8_LDA(At, 1, 0); PG8_STAGE(PG8_SA(0, 1), a2 + hA2, vA2);
;                 PG8_WAIT_V(8); PG8_WAIT_L(0); PG8_BAR; PG8_MMA(0, 0, At, B0); PG8_MMA(0, 1, At, B1); PG8_BAR; PG8_SCHED;
	s_setprio 3
	s_waitcnt lgkmcnt(0)
	v_mfma_f32_16x16x32_bf16 v[30:33], v[144:147], v[220:223], v[30:33]
	v_mfma_f32_16x16x32_bf16 v[30:33], v[148:151], v[224:227], v[30:33]
	v_mfma_f32_16x16x32_bf16 v[62:65], v[148:151], v[180:183], v[62:65]
	v_mfma_f32_16x16x32_bf16 v[62:65], v[144:147], v[176:179], v[62:65]
	v_mfma_f32_16x16x32_bf16 v[46:49], v[144:147], v[184:187], v[46:49]
	v_mfma_f32_16x16x32_bf16 v[46:49], v[148:151], v[216:219], v[46:49]
	v_mfma_f32_16x16x32_bf16 v[14:17], v[148:151], v[234:237], v[14:17]
	v_mfma_f32_16x16x32_bf16 v[14:17], v[144:147], v[230:233], v[14:17]
	v_mfma_f32_16x16x32_bf16 v[6:9], v[152:155], v[230:233], v[6:9]
	v_mfma_f32_16x16x32_bf16 v[6:9], v[156:159], v[234:237], v[6:9]
	v_mfma_f32_16x16x32_bf16 v[58:61], v[156:159], v[180:183], v[58:61]
	v_mfma_f32_16x16x32_bf16 v[58:61], v[152:155], v[176:179], v[58:61]
	v_mfma_f32_16x16x32_bf16 v[42:45], v[152:155], v[184:187], v[42:45]
	v_mfma_f32_16x16x32_bf16 v[42:45], v[156:159], v[216:219], v[42:45]
	v_mfma_f32_16x16x32_bf16 v[22:25], v[156:159], v[224:227], v[22:25]
	v_mfma_f32_16x16x32_bf16 v[22:25], v[152:155], v[220:223], v[22:25]
	s_setprio 0
	s_setprio 3
	v_mfma_f32_16x16x32_bf16 v[26:29], v[160:163], v[220:223], v[26:29]
	v_mfma_f32_16x16x32_bf16 v[26:29], v[164:167], v[224:227], v[26:29]
	v_mfma_f32_16x16x32_bf16 v[54:57], v[164:167], v[180:183], v[54:57]
	v_mfma_f32_16x16x32_bf16 v[54:57], v[160:163], v[176:179], v[54:57]
	v_mfma_f32_16x16x32_bf16 v[38:41], v[160:163], v[184:187], v[38:41]
	v_mfma_f32_16x16x32_bf16 v[38:41], v[164:167], v[216:219], v[38:41]
	v_mfma_f32_16x16x32_bf16 v[10:13], v[164:167], v[234:237], v[10:13]
	v_mfma_f32_16x16x32_bf16 v[10:13], v[160:163], v[230:233], v[10:13]
	v_mfma_f32_16x16x32_bf16 v[2:5], v[168:171], v[230:233], v[2:5]
	v_mfma_f32_16x16x32_bf16 v[2:5], v[172:175], v[234:237], v[2:5]
	v_mfma_f32_16x16x32_bf16 v[50:53], v[172:175], v[180:183], v[50:53]
	v_mfma_f32_16x16x32_bf16 v[50:53], v[168:171], v[176:179], v[50:53]
	v_mfma_f32_16x16x32_bf16 v[34:37], v[168:171], v[184:187], v[34:37]
	v_mfma_f32_16x16x32_bf16 v[34:37], v[172:175], v[216:219], v[34:37]
	v_mfma_f32_16x16x32_bf16 v[18:21], v[172:175], v[224:227], v[18:21]
	v_mfma_f32_16x16x32_bf16 v[18:21], v[168:171], v[220:223], v[18:21]
	s_setprio 0
	s_barrier
	s_add_i32 s60, 0, 0x18000
	v_add_u32_e32 v0, s60, v208
	v_add_u32_e32 v131, s60, v209
	ds_read_b128 v[144:147], v0
	ds_read_b128 v[148:151], v131
	v_add_u32_e32 v0, s66, v208
	s_add_i32 s61, 0, 0x1c000
	v_add_u32_e32 v131, s66, v209
	ds_read_b128 v[152:155], v0
	ds_read_b128 v[156:159], v131
	v_add_u32_e32 v0, s61, v208
	v_add_u32_e32 v131, s61, v209
	ds_read_b128 v[160:163], v0
	ds_read_b128 v[164:167], v131
	v_add_u32_e32 v0, s67, v208
	v_add_u32_e32 v131, s67, v209
	ds_read_b128 v[168:171], v0
	ds_read_b128 v[172:175], v131
	s_add_u32 s48, s58, s92
	s_addc_u32 s49, s59, s91
	s_mov_b32 m0, s34
	ds_read_b128 v[176:179], v212 offset:32768
	ds_read_b128 v[180:183], v212 offset:34816
	ds_read_b128 v[184:187], v213 offset:32768
	ds_read_b128 v[216:219], v213 offset:34816
	ds_read_b128 v[220:223], v212 offset:36864
	ds_read_b128 v[224:227], v212 offset:38912
	ds_read_b128 v[230:233], v213 offset:36864
	ds_read_b128 v[234:237], v213 offset:38912
	global_load_lds_dwordx4 v138, s[48:49]
	s_mov_b32 m0, s35
	s_nop 0
	global_load_lds_dwordx4 v140, s[48:49]
	s_waitcnt vmcnt(8)
	s_waitcnt lgkmcnt(0)
	s_barrier
	s_setprio 3
	s_waitcnt lgkmcnt(0)
	v_mfma_f32_16x16x32_bf16 v[94:97], v[144:147], v[220:223], v[94:97]
	v_mfma_f32_16x16x32_bf16 v[94:97], v[148:151], v[230:233], v[94:97]
	v_mfma_f32_16x16x32_bf16 v[126:129], v[148:151], v[184:187], v[126:129]
	v_mfma_f32_16x16x32_bf16 v[126:129], v[144:147], v[176:179], v[126:129]
	v_mfma_f32_16x16x32_bf16 v[110:113], v[144:147], v[180:183], v[110:113]
	v_mfma_f32_16x16x32_bf16 v[110:113], v[148:151], v[216:219], v[110:113]
	v_mfma_f32_16x16x32_bf16 v[78:81], v[148:151], v[234:237], v[78:81]
	v_mfma_f32_16x16x32_bf16 v[78:81], v[144:147], v[224:227], v[78:81]
	v_mfma_f32_16x16x32_bf16 v[74:77], v[152:155], v[224:227], v[74:77]
	v_mfma_f32_16x16x32_bf16 v[74:77], v[156:159], v[234:237], v[74:77]
	v_mfma_f32_16x16x32_bf16 v[122:125], v[156:159], v[184:187], v[122:125]
	v_mfma_f32_16x16x32_bf16 v[122:125], v[152:155], v[176:179], v[122:125]
	v_mfma_f32_16x16x32_bf16 v[106:109], v[152:155], v[180:183], v[106:109]
	v_mfma_f32_16x16x32_bf16 v[106:109], v[156:159], v[216:219], v[106:109]
	v_mfma_f32_16x16x32_bf16 v[90:93], v[156:159], v[230:233], v[90:93]
	v_mfma_f32_16x16x32_bf16 v[90:93], v[152:155], v[220:223], v[90:93]
	s_setprio 0
	s_setprio 3
	v_mfma_f32_16x16x32_bf16 v[86:89], v[160:163], v[220:223], v[86:89]
	v_mfma_f32_16x16x32_bf16 v[86:89], v[164:167], v[230:233], v[86:89]
	v_mfma_f32_16x16x32_bf16 v[118:121], v[164:167], v[184:187], v[118:121]
	v_mfma_f32_16x16x32_bf16 v[118:121], v[160:163], v[176:179], v[118:121]
	v_mfma_f32_16x16x32_bf16 v[102:105], v[160:163], v[180:183], v[102:105]
	v_mfma_f32_16x16x32_bf16 v[102:105], v[164:167], v[216:219], v[102:105]
	v_mfma_f32_16x16x32_bf16 v[70:73], v[164:167], v[234:237], v[70:73]
	v_mfma_f32_16x16x32_bf16 v[70:73], v[160:163], v[224:227], v[70:73]
	v_mfma_f32_16x16x32_bf16 v[66:69], v[168:171], v[224:227], v[66:69]
	v_mfma_f32_16x16x32_bf16 v[66:69], v[172:175], v[234:237], v[66:69]
	v_mfma_f32_16x16x32_bf16 v[114:117], v[172:175], v[184:187], v[114:117]
	v_mfma_f32_16x16x32_bf16 v[114:117], v[168:171], v[176:179], v[114:117]
	v_mfma_f32_16x16x32_bf16 v[98:101], v[168:171], v[180:183], v[98:101]
	v_mfma_f32_16x16x32_bf16 v[98:101], v[172:175], v[216:219], v[98:101]
	v_mfma_f32_16x16x32_bf16 v[82:85], v[172:175], v[230:233], v[82:85]
	v_mfma_f32_16x16x32_bf16 v[82:85], v[168:171], v[220:223], v[82:85]
	s_setprio 0
	s_barrier
; #define PG8_STAGE(bufoff, gbase, voff) do { _Pragma("unroll") for (int _i = 0; _i < 2; ++_i) \
;         __builtin_amdgcn_global_load_lds((const unsigned*)((const char*)(gbase) + (voff)[_i]), (LAS unsigned*)(lds + (bufoff) + ldsw + _i * 8192), 16, 0, 0); } while (0)
; #define PG8_LDA(dst, b, h) do { _Pragma("unroll") for (int m = 0; m < 4; ++m) _Pragma("unroll") for (int k = 0; k < 2; ++k) dst[m][k] = *(const LAS bf16x8*)(lds + PG8_SA(b, h) + aoffk[k] + m * 2048); } while (0)
; #define PG8_WAIT_V(n) asm volatile("s_waitcnt vmcnt(" #n ")" ::: "memory")
; #define PG8_WAIT_L(n) asm volatile("s_waitcnt lgkmcnt(" #n ")" ::: "memory")
; #define PG8_BAR __builtin_amdgcn_s_barrier()
; #define PG8_SCHED __builtin_amdgcn_sched_barrier(0)
;     __device__ __forceinline__ void mid(Acc& acc, const Unit& u, int s, int wr, int wc, int fr, int fq) const {
;         int lo = (wr * 4 + wc) * 8192 + (fq * 16 + fr) * 16; asm volatile("" : "+v"(lo));
;         const unsigned char* gp = gate + ((size_t)(u.pm * 48 + s * 16 + u.pn) << 16) + lo;
;         u32x4 G[8][2];
; #pragma unroll
;         for (int i = 0; i < 8; ++i) { G[i][0] = __builtin_nontemporal_load((const u32x4*)(gp + i * 1024)); G[i][1] = __builtin_nontemporal_load((const u32x4*)(gp + (1 << 20) + i * 1024)); }
; template <class Epi, class Sched, class GemmT>
; __device__ __forceinline__ void gemm_phase(LAS unsigned char* lds, const GemmT& g, const Sched& S, const Epi& E, const int wid) {
;     ...
;                 PG8_LDA(At, 1, 1); PG8_STAGE(PG8_SB(1, 0), b3, vB2); PG8_STAGE(PG8_SB(1, 1), b3 + hB2, vB2); PG8_STAGE(PG8_SA(1, 0), a3, vA2);
;                 PG8_WAIT_V(8); PG8_WAIT_L(0); PG8_BAR; PG8_MMA(1, 0, At, B0); PG8_MMA(1, 1, At, B1); PG8_BAR; PG8_SCHED;
;             }
;             if constexpr (NSEG > 1) { if (sgi + 1 < NSEG) E.mid(acc, cur, sgi, wr, wc, fr, fq); }
	s_add_i32 s48, s60, s68
	v_lshl_add_u64 v[202:203], v[202:203], 0, s[20:21]
	s_mov_b32 m0, s48
	ds_read_b128 v[138:141], v212 offset:49152
	ds_read_b128 v[176:179], v212 offset:51200
	ds_read_b128 v[180:183], v213 offset:49152
	ds_read_b128 v[184:187], v213 offset:51200
	ds_read_b128 v[216:219], v212 offset:53248
	ds_read_b128 v[220:223], v212 offset:55296
	ds_read_b128 v[224:227], v213 offset:53248
	ds_read_b128 v[230:233], v213 offset:55296
	global_load_lds_dwordx4 v[202:203], off
	v_lshl_add_u64 v[202:203], v[238:239], 0, s[20:21]
	s_add_i32 m0, s48, 0x2000
	s_add_i32 s48, s61, s68
	global_load_lds_dwordx4 v[202:203], off
	v_lshl_add_u64 v[202:203], v[240:241], 0, s[20:21]
	s_mov_b32 m0, s48
	v_lshl_add_u64 v[188:189], v[188:189], 0, s[20:21]
	global_load_lds_dwordx4 v[202:203], off
	v_lshl_add_u64 v[202:203], v[242:243], 0, s[20:21]
	s_add_i32 m0, s48, 0x2000
	s_nop 0
	global_load_lds_dwordx4 v[202:203], off
	s_mov_b32 m0, s54
	s_nop 0
	global_load_lds_dwordx4 v[188:189], off
	v_lshl_add_u64 v[188:189], v[244:245], 0, s[20:21]
	s_mov_b32 m0, s55
	s_nop 0
	global_load_lds_dwordx4 v[188:189], off
	s_waitcnt vmcnt(8)
	s_waitcnt lgkmcnt(0)
	s_barrier
	s_setprio 3
	s_waitcnt lgkmcnt(0)
	v_mfma_f32_16x16x32_bf16 v[14:17], v[144:147], v[220:223], v[14:17]
	v_mfma_f32_16x16x32_bf16 v[14:17], v[148:151], v[230:233], v[14:17]
	v_mfma_f32_16x16x32_bf16 v[62:65], v[148:151], v[180:183], v[62:65]
	v_mfma_f32_16x16x32_bf16 v[62:65], v[144:147], v[138:141], v[62:65]
	v_mfma_f32_16x16x32_bf16 v[46:49], v[144:147], v[176:179], v[46:49]
	v_mfma_f32_16x16x32_bf16 v[46:49], v[148:151], v[184:187], v[46:49]
	v_mfma_f32_16x16x32_bf16 v[30:33], v[148:151], v[224:227], v[30:33]
	v_mfma_f32_16x16x32_bf16 v[30:33], v[144:147], v[216:219], v[30:33]
	v_mfma_f32_16x16x32_bf16 v[22:25], v[152:155], v[216:219], v[22:25]
	v_mfma_f32_16x16x32_bf16 v[22:25], v[156:159], v[224:227], v[22:25]
	v_mfma_f32_16x16x32_bf16 v[58:61], v[156:159], v[180:183], v[58:61]
	v_mfma_f32_16x16x32_bf16 v[58:61], v[152:155], v[138:141], v[58:61]
	v_mfma_f32_16x16x32_bf16 v[42:45], v[152:155], v[176:179], v[42:45]
	v_mfma_f32_16x16x32_bf16 v[42:45], v[156:159], v[184:187], v[42:45]
	v_mfma_f32_16x16x32_bf16 v[6:9], v[156:159], v[230:233], v[6:9]
	v_mfma_f32_16x16x32_bf16 v[6:9], v[152:155], v[220:223], v[6:9]
	s_setprio 0
	s_setprio 3
	v_mfma_f32_16x16x32_bf16 v[10:13], v[160:163], v[220:223], v[10:13]
	v_mfma_f32_16x16x32_bf16 v[10:13], v[164:167], v[230:233], v[10:13]
	v_mfma_f32_16x16x32_bf16 v[54:57], v[164:167], v[180:183], v[54:57]
	v_mfma_f32_16x16x32_bf16 v[54:57], v[160:163], v[138:141], v[54:57]
	v_mfma_f32_16x16x32_bf16 v[38:41], v[160:163], v[176:179], v[38:41]
	v_mfma_f32_16x16x32_bf16 v[38:41], v[164:167], v[184:187], v[38:41]
	v_mfma_f32_16x16x32_bf16 v[26:29], v[164:167], v[224:227], v[26:29]
	v_mfma_f32_16x16x32_bf16 v[26:29], v[160:163], v[216:219], v[26:29]
	v_mfma_f32_16x16x32_bf16 v[18:21], v[168:171], v[216:219], v[18:21]
	v_mfma_f32_16x16x32_bf16 v[18:21], v[172:175], v[224:227], v[18:21]
	v_mfma_f32_16x16x32_bf16 v[50:53], v[172:175], v[180:183], v[50:53]
	v_mfma_f32_16x16x32_bf16 v[50:53], v[168:171], v[138:141], v[50:53]
	v_mfma_f32_16x16x32_bf16 v[34:37], v[168:171], v[176:179], v[34:37]
	v_mfma_f32_16x16x32_bf16 v[34:37], v[172:175], v[184:187], v[34:37]
	v_mfma_f32_16x16x32_bf16 v[2:5], v[172:175], v[230:233], v[2:5]
	v_mfma_f32_16x16x32_bf16 v[2:5], v[168:171], v[220:223], v[2:5]
	s_setprio 0
	s_barrier
	s_add_u32 s56, s56, 0x100
	s_addc_u32 s57, s57, 0
	s_cmp_ge_u32 s90, s42
	s_cbranch_scc0 .LBB0_764
	s_and_b64 vcc, exec, s[52:53]
	s_cbranch_vccz .LBB0_767
	s_lshl_b32 s42, s83, 4
	s_add_i32 s42, s82, s42
	s_ashr_i32 s43, s42, 31
	s_lshl_b64 s[42:43], s[42:43], 16
	v_mov_b32_e32 v130, v210
	s_add_u32 s42, s22, s42
	s_addc_u32 s43, s23, s43
	v_ashrrev_i32_e32 v131, 31, v130
	v_lshl_add_u64 v[130:131], s[42:43], 0, v[130:131]
	v_add_co_u32_e32 v132, vcc, s69, v130
	s_mov_b32 s42, 0x101000
	s_nop 0
	v_addc_co_u32_e32 v133, vcc, 0, v131, vcc
	global_load_dwordx4 v[186:189], v[130:131], off nt
	v_add_co_u32_e32 v134, vcc, s42, v130
	s_movk_i32 s42, 0x1000
	s_nop 0
	v_addc_co_u32_e32 v135, vcc, 0, v131, vcc
	global_load_dwordx4 v[216:219], v[134:135], off offset:-4096 nt
	global_load_dwordx4 v[178:181], v[130:131], off offset:1024 nt
	global_load_dwordx4 v[182:185], v[132:133], off offset:1024 nt
	global_load_dwordx4 v[170:173], v[130:131], off offset:2048 nt
	global_load_dwordx4 v[174:177], v[132:133], off offset:2048 nt
	global_load_dwordx4 v[162:165], v[130:131], off offset:3072 nt
	global_load_dwordx4 v[166:169], v[132:133], off offset:3072 nt
	v_add_co_u32_e32 v130, vcc, s42, v130
	s_waitcnt vmcnt(0)
;     __device__ __forceinline__ void mid(Acc& acc, const Unit& u, int s, int wr, int wc, int fr, int fq) const {
;     ...
;         for (int i = 0; i < 8; ++i) { G[i][0] = __builtin_nontemporal_load((const u32x4*)(gp + i * 1024)); G[i][1] = __builtin_nontemporal_load((const u32x4*)(gp + (1 << 20) + i * 1024)); }
; #pragma unroll
;         for (int i = 0; i < 8; ++i) { const int ai = i >> 2, m = i & 3;
; #pragma unroll
;             for (int bj = 0; bj < 2; ++bj) {
;                 const u32x4 ga = G[i][0], gb = G[i][1];
;                 const u32x2 wa = bj == 0 ? (u32x2){ga.x, ga.y} : (u32x2){ga.z, ga.w}, wb = bj == 0 ? (u32x2){gb.x, gb.y} : (u32x2){gb.z, gb.w};
;                 float fa[8], fb[8]; gate_unpack8(wa, fa); gate_unpack8(wb, fb);
; #pragma unroll
;                 for (int e = 0; e < 8; ++e) fa[e] = fa[e] * __builtin_amdgcn_rcpf(fb[e]);
;                 f32x4& v0 = acc[ai][bj][m][0]; f32x4& v1 = acc[ai][bj][m][1];
;                 v0[0] *= fa[0]; v0[1] *= fa[1]; v0[2] *= fa[2]; v0[3] *= fa[3]; v1[0] *= fa[4]; v1[1] *= fa[5]; v1[2] *= fa[6]; v1[3] *= fa[7]; }
;             __builtin_amdgcn_sched_barrier(0); }
	v_cvt_f32_ubyte0_e32 v0, v216
	v_addc_co_u32_e32 v131, vcc, 0, v131, vcc
	global_load_dwordx4 v[154:157], v[130:131], off nt
	global_load_dwordx4 v[158:161], v[134:135], off nt
	global_load_dwordx4 v[146:149], v[130:131], off offset:1024 nt
	global_load_dwordx4 v[150:153], v[134:135], off offset:1024 nt
	global_load_dwordx4 v[138:141], v[130:131], off offset:2048 nt
	global_load_dwordx4 v[142:145], v[134:135], off offset:2048 nt
	s_nop 0
	global_load_dwordx4 v[130:133], v[130:131], off offset:3072 nt
	s_nop 0
	global_load_dwordx4 v[134:137], v[134:135], off offset:3072 nt
	v_cvt_f32_ubyte1_e32 v203, v216
	v_cvt_f32_ubyte2_e32 v215, v216
	v_cvt_f32_ubyte3_e32 v220, v216
	v_cvt_f32_ubyte0_e32 v221, v217
	v_cvt_f32_ubyte1_e32 v222, v217
	v_cvt_f32_ubyte2_e32 v223, v217
	v_cvt_f32_ubyte3_e32 v224, v217
	v_rcp_iflag_f32_e32 v202, v0
	v_rcp_iflag_f32_e32 v203, v203
	v_rcp_iflag_f32_e32 v216, v215
	v_rcp_iflag_f32_e32 v217, v220
	v_rcp_iflag_f32_e32 v220, v221
	v_rcp_iflag_f32_e32 v221, v222
	v_rcp_iflag_f32_e32 v222, v223
	v_rcp_iflag_f32_e32 v223, v224
	v_cvt_f32_ubyte3_e32 v225, v186
	v_cvt_f32_ubyte2_e32 v224, v186
	v_cvt_f32_ubyte1_e32 v227, v186
	v_cvt_f32_ubyte0_e32 v226, v186
	v_pk_mul_f32 v[202:203], v[202:203], v[226:227]
	v_pk_mul_f32 v[216:217], v[216:217], v[224:225]
	v_pk_mul_f32 v[126:127], v[126:127], v[202:203]
	v_pk_mul_f32 v[128:129], v[128:129], v[216:217]
	v_cvt_f32_ubyte3_e32 v203, v187
	v_cvt_f32_ubyte2_e32 v202, v187
	v_cvt_f32_ubyte1_e32 v217, v187
	v_cvt_f32_ubyte0_e32 v216, v187
	v_pk_mul_f32 v[186:187], v[220:221], v[216:217]
	v_pk_mul_f32 v[202:203], v[222:223], v[202:203]
	v_pk_mul_f32 v[122:123], v[122:123], v[186:187]
	v_pk_mul_f32 v[124:125], v[124:125], v[202:203]
	v_cvt_f32_ubyte0_e32 v0, v218
	v_cvt_f32_ubyte1_e32 v186, v218
	v_cvt_f32_ubyte2_e32 v187, v218
	v_cvt_f32_ubyte3_e32 v202, v218
	v_cvt_f32_ubyte0_e32 v203, v219
	v_cvt_f32_ubyte1_e32 v215, v219
	v_cvt_f32_ubyte2_e32 v220, v219
	v_cvt_f32_ubyte3_e32 v221, v219
	v_rcp_iflag_f32_e32 v216, v0
	v_rcp_iflag_f32_e32 v217, v186
	v_rcp_iflag_f32_e32 v218, v187
	v_rcp_iflag_f32_e32 v219, v202
	v_rcp_iflag_f32_e32 v202, v203
	v_rcp_iflag_f32_e32 v203, v215
	v_rcp_iflag_f32_e32 v186, v220
	v_rcp_iflag_f32_e32 v187, v221
	v_cvt_f32_ubyte3_e32 v221, v188
	v_cvt_f32_ubyte2_e32 v220, v188
	v_cvt_f32_ubyte1_e32 v223, v188
	v_cvt_f32_ubyte0_e32 v222, v188
	v_pk_mul_f32 v[216:217], v[216:217], v[222:223]
	v_pk_mul_f32 v[218:219], v[218:219], v[220:221]
	v_pk_mul_f32 v[118:119], v[118:119], v[216:217]
	v_pk_mul_f32 v[120:121], v[120:121], v[218:219]
	v_cvt_f32_ubyte3_e32 v217, v189
	v_cvt_f32_ubyte2_e32 v216, v189
	v_cvt_f32_ubyte1_e32 v219, v189
	v_cvt_f32_ubyte0_e32 v218, v189
	v_pk_mul_f32 v[188:189], v[202:203], v[218:219]
	v_pk_mul_f32 v[186:187], v[186:187], v[216:217]
	v_pk_mul_f32 v[114:115], v[114:115], v[188:189]
	v_pk_mul_f32 v[116:117], v[116:117], v[186:187]
	v_cvt_f32_ubyte0_e32 v0, v182
	v_cvt_f32_ubyte1_e32 v186, v182
	v_cvt_f32_ubyte2_e32 v187, v182
	v_cvt_f32_ubyte3_e32 v188, v182
	v_cvt_f32_ubyte0_e32 v189, v183
	v_cvt_f32_ubyte1_e32 v202, v183
	v_cvt_f32_ubyte2_e32 v203, v183
	v_cvt_f32_ubyte3_e32 v215, v183
	v_rcp_iflag_f32_e32 v182, v0
	v_rcp_iflag_f32_e32 v183, v186
	v_rcp_iflag_f32_e32 v186, v187
	v_rcp_iflag_f32_e32 v187, v188
	v_rcp_iflag_f32_e32 v188, v189
	v_rcp_iflag_f32_e32 v189, v202
	v_rcp_iflag_f32_e32 v202, v203
	v_rcp_iflag_f32_e32 v203, v215
	v_cvt_f32_ubyte3_e32 v217, v178
	v_cvt_f32_ubyte2_e32 v216, v178
	v_cvt_f32_ubyte1_e32 v219, v178
	v_cvt_f32_ubyte0_e32 v218, v178
	v_pk_mul_f32 v[182:183], v[182:183], v[218:219]
	v_pk_mul_f32 v[186:187], v[186:187], v[216:217]
	v_pk_mul_f32 v[110:111], v[110:111], v[182:183]
	v_pk_mul_f32 v[112:113], v[112:113], v[186:187]
	v_cvt_f32_ubyte3_e32 v183, v179
	v_cvt_f32_ubyte2_e32 v182, v179
	v_cvt_f32_ubyte1_e32 v187, v179
	v_cvt_f32_ubyte0_e32 v186, v179
	v_pk_mul_f32 v[178:179], v[188:189], v[186:187]
	v_pk_mul_f32 v[182:183], v[202:203], v[182:183]
	v_pk_mul_f32 v[106:107], v[106:107], v[178:179]
	v_pk_mul_f32 v[108:109], v[108:109], v[182:183]
	v_cvt_f32_ubyte0_e32 v0, v184
	v_cvt_f32_ubyte1_e32 v179, v184
	v_cvt_f32_ubyte2_e32 v182, v184
	v_cvt_f32_ubyte3_e32 v183, v184
	v_rcp_iflag_f32_e32 v178, v0
	v_rcp_iflag_f32_e32 v179, v179
	v_rcp_iflag_f32_e32 v182, v182
	v_rcp_iflag_f32_e32 v183, v183
	v_cvt_f32_ubyte0_e32 v184, v185
	v_cvt_f32_ubyte1_e32 v186, v185
	v_cvt_f32_ubyte2_e32 v187, v185
	v_cvt_f32_ubyte3_e32 v188, v185
	v_rcp_iflag_f32_e32 v184, v184
	v_rcp_iflag_f32_e32 v185, v186
	v_rcp_iflag_f32_e32 v186, v187
	v_rcp_iflag_f32_e32 v187, v188
	v_cvt_f32_ubyte3_e32 v189, v180
	v_cvt_f32_ubyte2_e32 v188, v180
	v_cvt_f32_ubyte1_e32 v203, v180
	v_cvt_f32_ubyte0_e32 v202, v180
	v_pk_mul_f32 v[178:179], v[178:179], v[202:203]
	v_pk_mul_f32 v[182:183], v[182:183], v[188:189]
	v_pk_mul_f32 v[102:103], v[102:103], v[178:179]
	v_pk_mul_f32 v[104:105], v[104:105], v[182:183]
	v_cvt_f32_ubyte3_e32 v179, v181
	v_cvt_f32_ubyte2_e32 v178, v181
	v_cvt_f32_ubyte1_e32 v183, v181
	v_cvt_f32_ubyte0_e32 v182, v181
	v_pk_mul_f32 v[180:181], v[184:185], v[182:183]
	v_pk_mul_f32 v[178:179], v[186:187], v[178:179]
	v_pk_mul_f32 v[98:99], v[98:99], v[180:181]
	v_pk_mul_f32 v[100:101], v[100:101], v[178:179]
	v_cvt_f32_ubyte0_e32 v0, v174
	v_cvt_f32_ubyte1_e32 v178, v174
	v_cvt_f32_ubyte2_e32 v179, v174
	v_cvt_f32_ubyte3_e32 v180, v174
	v_cvt_f32_ubyte0_e32 v181, v175
	v_cvt_f32_ubyte1_e32 v182, v175
	v_cvt_f32_ubyte2_e32 v183, v175
	v_cvt_f32_ubyte3_e32 v184, v175
	v_rcp_iflag_f32_e32 v174, v0
	v_rcp_iflag_f32_e32 v175, v178
	v_rcp_iflag_f32_e32 v178, v179
	v_rcp_iflag_f32_e32 v179, v180
	v_rcp_iflag_f32_e32 v180, v181
;     __device__ __forceinline__ void mid(Acc& acc, const Unit& u, int s, int wr, int wc, int fr, int fq) const {
;     ...
;         for (int i = 0; i < 8; ++i) { const int ai = i >> 2, m = i & 3;
; #pragma unroll
;             for (int bj = 0; bj < 2; ++bj) {
;                 const u32x4 ga = G[i][0], gb = G[i][1];
;                 const u32x2 wa = bj == 0 ? (u32x2){ga.x, ga.y} : (u32x2){ga.z, ga.w}, wb = bj == 0 ? (u32x2){gb.x, gb.y} : (u32x2){gb.z, gb.w};
;                 float fa[8], fb[8]; gate_unpack8(wa, fa); gate_unpack8(wb, fb);
; #pragma unroll
;                 for (int e = 0; e < 8; ++e) fa[e] = fa[e] * __builtin_amdgcn_rcpf(fb[e]);
;                 f32x4& v0 = acc[ai][bj][m][0]; f32x4& v1 = acc[ai][bj][m][1];
;                 v0[0] *= fa[0]; v0[1] *= fa[1]; v0[2] *= fa[2]; v0[3] *= fa[3]; v1[0] *= fa[4]; v1[1] *= fa[5]; v1[2] *= fa[6]; v1[3] *= fa[7]; }
;             __builtin_amdgcn_sched_barrier(0); }
	v_rcp_iflag_f32_e32 v181, v182
	v_rcp_iflag_f32_e32 v182, v183
	v_rcp_iflag_f32_e32 v183, v184
	v_cvt_f32_ubyte3_e32 v185, v170
	v_cvt_f32_ubyte2_e32 v184, v170
	v_cvt_f32_ubyte1_e32 v187, v170
	v_cvt_f32_ubyte0_e32 v186, v170
	v_pk_mul_f32 v[174:175], v[174:175], v[186:187]
	v_pk_mul_f32 v[178:179], v[178:179], v[184:185]
	v_pk_mul_f32 v[94:95], v[94:95], v[174:175]
	v_pk_mul_f32 v[96:97], v[96:97], v[178:179]
	v_cvt_f32_ubyte3_e32 v175, v171
	v_cvt_f32_ubyte2_e32 v174, v171
	v_cvt_f32_ubyte1_e32 v179, v171
	v_cvt_f32_ubyte0_e32 v178, v171
	v_pk_mul_f32 v[170:171], v[180:181], v[178:179]
	v_pk_mul_f32 v[174:175], v[182:183], v[174:175]
	v_pk_mul_f32 v[90:91], v[90:91], v[170:171]
	v_pk_mul_f32 v[92:93], v[92:93], v[174:175]
	v_cvt_f32_ubyte0_e32 v0, v176
	v_cvt_f32_ubyte1_e32 v171, v176
	v_cvt_f32_ubyte2_e32 v174, v176
	v_cvt_f32_ubyte3_e32 v175, v176
	v_rcp_iflag_f32_e32 v170, v0
	v_rcp_iflag_f32_e32 v171, v171
	v_rcp_iflag_f32_e32 v174, v174
	v_rcp_iflag_f32_e32 v175, v175
	v_cvt_f32_ubyte0_e32 v176, v177
	v_cvt_f32_ubyte1_e32 v178, v177
	v_cvt_f32_ubyte2_e32 v179, v177
	v_cvt_f32_ubyte3_e32 v180, v177
	v_rcp_iflag_f32_e32 v176, v176
	v_rcp_iflag_f32_e32 v177, v178
	v_rcp_iflag_f32_e32 v178, v179
	v_rcp_iflag_f32_e32 v179, v180
	v_cvt_f32_ubyte3_e32 v181, v172
	v_cvt_f32_ubyte2_e32 v180, v172
	v_cvt_f32_ubyte1_e32 v183, v172
	v_cvt_f32_ubyte0_e32 v182, v172
	v_pk_mul_f32 v[170:171], v[170:171], v[182:183]
	v_pk_mul_f32 v[174:175], v[174:175], v[180:181]
	v_pk_mul_f32 v[86:87], v[86:87], v[170:171]
	v_pk_mul_f32 v[88:89], v[88:89], v[174:175]
	v_cvt_f32_ubyte3_e32 v171, v173
	v_cvt_f32_ubyte2_e32 v170, v173
	v_cvt_f32_ubyte1_e32 v175, v173
	v_cvt_f32_ubyte0_e32 v174, v173
	v_pk_mul_f32 v[172:173], v[176:177], v[174:175]
	v_pk_mul_f32 v[170:171], v[178:179], v[170:171]
	v_pk_mul_f32 v[82:83], v[82:83], v[172:173]
	v_pk_mul_f32 v[84:85], v[84:85], v[170:171]
	v_cvt_f32_ubyte0_e32 v0, v166
	v_cvt_f32_ubyte1_e32 v170, v166
	v_cvt_f32_ubyte2_e32 v171, v166
	v_cvt_f32_ubyte3_e32 v172, v166
	v_cvt_f32_ubyte0_e32 v173, v167
	v_cvt_f32_ubyte1_e32 v174, v167
	v_cvt_f32_ubyte2_e32 v175, v167
	v_cvt_f32_ubyte3_e32 v176, v167
	v_rcp_iflag_f32_e32 v166, v0
	v_rcp_iflag_f32_e32 v167, v170
	v_rcp_iflag_f32_e32 v170, v171
	v_rcp_iflag_f32_e32 v171, v172
	v_rcp_iflag_f32_e32 v172, v173
	v_rcp_iflag_f32_e32 v173, v174
	v_rcp_iflag_f32_e32 v174, v175
	v_rcp_iflag_f32_e32 v175, v176
	v_cvt_f32_ubyte3_e32 v177, v162
	v_cvt_f32_ubyte2_e32 v176, v162
	v_cvt_f32_ubyte1_e32 v179, v162
	v_cvt_f32_ubyte0_e32 v178, v162
	v_pk_mul_f32 v[166:167], v[166:167], v[178:179]
	v_pk_mul_f32 v[170:171], v[170:171], v[176:177]
	v_pk_mul_f32 v[78:79], v[78:79], v[166:167]
	v_pk_mul_f32 v[80:81], v[80:81], v[170:171]
	v_cvt_f32_ubyte3_e32 v167, v163
	v_cvt_f32_ubyte2_e32 v166, v163
	v_cvt_f32_ubyte1_e32 v171, v163
	v_cvt_f32_ubyte0_e32 v170, v163
	v_pk_mul_f32 v[162:163], v[172:173], v[170:171]
	v_pk_mul_f32 v[166:167], v[174:175], v[166:167]
	v_pk_mul_f32 v[74:75], v[74:75], v[162:163]
	v_pk_mul_f32 v[76:77], v[76:77], v[166:167]
	v_cvt_f32_ubyte0_e32 v0, v168
	v_cvt_f32_ubyte1_e32 v163, v168
	v_cvt_f32_ubyte2_e32 v166, v168
	v_cvt_f32_ubyte3_e32 v167, v168
	v_rcp_iflag_f32_e32 v162, v0
	v_rcp_iflag_f32_e32 v163, v163
	v_rcp_iflag_f32_e32 v166, v166
	v_rcp_iflag_f32_e32 v167, v167
	v_cvt_f32_ubyte0_e32 v168, v169
	v_cvt_f32_ubyte1_e32 v170, v169
	v_cvt_f32_ubyte2_e32 v171, v169
	v_cvt_f32_ubyte3_e32 v172, v169
	v_rcp_iflag_f32_e32 v168, v168
	v_rcp_iflag_f32_e32 v169, v170
	v_rcp_iflag_f32_e32 v170, v171
	v_rcp_iflag_f32_e32 v171, v172
	v_cvt_f32_ubyte3_e32 v173, v164
	v_cvt_f32_ubyte2_e32 v172, v164
	v_cvt_f32_ubyte1_e32 v175, v164
	v_cvt_f32_ubyte0_e32 v174, v164
	v_pk_mul_f32 v[162:163], v[162:163], v[174:175]
	v_pk_mul_f32 v[166:167], v[166:167], v[172:173]
	v_pk_mul_f32 v[70:71], v[70:71], v[162:163]
	v_pk_mul_f32 v[72:73], v[72:73], v[166:167]
	v_cvt_f32_ubyte3_e32 v163, v165
	v_cvt_f32_ubyte2_e32 v162, v165
	v_cvt_f32_ubyte1_e32 v167, v165
	v_cvt_f32_ubyte0_e32 v166, v165
	v_pk_mul_f32 v[164:165], v[168:169], v[166:167]
	v_pk_mul_f32 v[162:163], v[170:171], v[162:163]
	v_pk_mul_f32 v[66:67], v[66:67], v[164:165]
	v_pk_mul_f32 v[68:69], v[68:69], v[162:163]
	s_waitcnt vmcnt(6)
	v_cvt_f32_ubyte0_e32 v0, v158
	v_cvt_f32_ubyte1_e32 v162, v158
	v_cvt_f32_ubyte2_e32 v163, v158
	v_cvt_f32_ubyte3_e32 v164, v158
	v_cvt_f32_ubyte0_e32 v165, v159
	v_cvt_f32_ubyte1_e32 v166, v159
	v_cvt_f32_ubyte2_e32 v167, v159
	v_cvt_f32_ubyte3_e32 v168, v159
	v_rcp_iflag_f32_e32 v158, v0
	v_rcp_iflag_f32_e32 v159, v162
	v_rcp_iflag_f32_e32 v162, v163
	v_rcp_iflag_f32_e32 v163, v164
	v_rcp_iflag_f32_e32 v164, v165
	v_rcp_iflag_f32_e32 v165, v166
	v_rcp_iflag_f32_e32 v166, v167
	v_rcp_iflag_f32_e32 v167, v168
	v_cvt_f32_ubyte3_e32 v169, v154
	v_cvt_f32_ubyte2_e32 v168, v154
	v_cvt_f32_ubyte1_e32 v171, v154
	v_cvt_f32_ubyte0_e32 v170, v154
	v_pk_mul_f32 v[158:159], v[158:159], v[170:171]
	v_pk_mul_f32 v[162:163], v[162:163], v[168:169]
	v_pk_mul_f32 v[62:63], v[62:63], v[158:159]
	v_pk_mul_f32 v[64:65], v[64:65], v[162:163]
	v_cvt_f32_ubyte3_e32 v159, v155
	v_cvt_f32_ubyte2_e32 v158, v155
	v_cvt_f32_ubyte1_e32 v163, v155
	v_cvt_f32_ubyte0_e32 v162, v155
	v_pk_mul_f32 v[154:155], v[164:165], v[162:163]
	v_pk_mul_f32 v[158:159], v[166:167], v[158:159]
	v_pk_mul_f32 v[58:59], v[58:59], v[154:155]
	v_pk_mul_f32 v[60:61], v[60:61], v[158:159]
	v_cvt_f32_ubyte0_e32 v0, v160
	v_cvt_f32_ubyte1_e32 v155, v160
	v_cvt_f32_ubyte2_e32 v158, v160
	v_cvt_f32_ubyte3_e32 v159, v160
	v_rcp_iflag_f32_e32 v154, v0
	v_rcp_iflag_f32_e32 v155, v155
	v_rcp_iflag_f32_e32 v158, v158
	v_rcp_iflag_f32_e32 v159, v159
	v_cvt_f32_ubyte0_e32 v160, v161
	v_cvt_f32_ubyte1_e32 v162, v161
	v_cvt_f32_ubyte2_e32 v163, v161
	v_cvt_f32_ubyte3_e32 v164, v161
	v_rcp_iflag_f32_e32 v160, v160
	v_rcp_iflag_f32_e32 v161, v162
	v_rcp_iflag_f32_e32 v162, v163
	v_rcp_iflag_f32_e32 v163, v164
	v_cvt_f32_ubyte3_e32 v165, v156
	v_cvt_f32_ubyte2_e32 v164, v156
	v_cvt_f32_ubyte1_e32 v167, v156
	v_cvt_f32_ubyte0_e32 v166, v156
	v_pk_mul_f32 v[154:155], v[154:155], v[166:167]
	v_pk_mul_f32 v[158:159], v[158:159], v[164:165]
	v_pk_mul_f32 v[54:55], v[54:55], v[154:155]
	v_pk_mul_f32 v[56:57], v[56:57], v[158:159]
	v_cvt_f32_ubyte3_e32 v155, v157
	v_cvt_f32_ubyte2_e32 v154, v157
	v_cvt_f32_ubyte1_e32 v159, v157
	v_cvt_f32_ubyte0_e32 v158, v157
	v_pk_mul_f32 v[156:157], v[160:161], v[158:159]
	v_pk_mul_f32 v[154:155], v[162:163], v[154:155]
	v_pk_mul_f32 v[50:51], v[50:51], v[156:157]
	v_pk_mul_f32 v[52:53], v[52:53], v[154:155]
	s_waitcnt vmcnt(4)
;     __device__ __forceinline__ void mid(Acc& acc, const Unit& u, int s, int wr, int wc, int fr, int fq) const {
;     ...
;         for (int i = 0; i < 8; ++i) { const int ai = i >> 2, m = i & 3;
; #pragma unroll
;             for (int bj = 0; bj < 2; ++bj) {
;                 const u32x4 ga = G[i][0], gb = G[i][1];
;                 const u32x2 wa = bj == 0 ? (u32x2){ga.x, ga.y} : (u32x2){ga.z, ga.w}, wb = bj == 0 ? (u32x2){gb.x, gb.y} : (u32x2){gb.z, gb.w};
;                 float fa[8], fb[8]; gate_unpack8(wa, fa); gate_unpack8(wb, fb);
; #pragma unroll
;                 for (int e = 0; e < 8; ++e) fa[e] = fa[e] * __builtin_amdgcn_rcpf(fb[e]);
;                 f32x4& v0 = acc[ai][bj][m][0]; f32x4& v1 = acc[ai][bj][m][1];
;                 v0[0] *= fa[0]; v0[1] *= fa[1]; v0[2] *= fa[2]; v0[3] *= fa[3]; v1[0] *= fa[4]; v1[1] *= fa[5]; v1[2] *= fa[6]; v1[3] *= fa[7]; }
;             __builtin_amdgcn_sched_barrier(0); }
	v_cvt_f32_ubyte0_e32 v0, v150
	v_cvt_f32_ubyte1_e32 v154, v150
	v_cvt_f32_ubyte2_e32 v155, v150
	v_cvt_f32_ubyte3_e32 v156, v150
	v_cvt_f32_ubyte0_e32 v157, v151
	v_cvt_f32_ubyte1_e32 v158, v151
	v_cvt_f32_ubyte2_e32 v159, v151
	v_cvt_f32_ubyte3_e32 v160, v151
	v_rcp_iflag_f32_e32 v150, v0
	v_rcp_iflag_f32_e32 v151, v154
	v_rcp_iflag_f32_e32 v154, v155
	v_rcp_iflag_f32_e32 v155, v156
	v_rcp_iflag_f32_e32 v156, v157
	v_rcp_iflag_f32_e32 v157, v158
	v_rcp_iflag_f32_e32 v158, v159
	v_rcp_iflag_f32_e32 v159, v160
	v_cvt_f32_ubyte3_e32 v161, v146
	v_cvt_f32_ubyte2_e32 v160, v146
	v_cvt_f32_ubyte1_e32 v163, v146
	v_cvt_f32_ubyte0_e32 v162, v146
	v_pk_mul_f32 v[150:151], v[150:151], v[162:163]
	v_pk_mul_f32 v[154:155], v[154:155], v[160:161]
	v_pk_mul_f32 v[46:47], v[46:47], v[150:151]
	v_pk_mul_f32 v[48:49], v[48:49], v[154:155]
	v_cvt_f32_ubyte3_e32 v151, v147
	v_cvt_f32_ubyte2_e32 v150, v147
	v_cvt_f32_ubyte1_e32 v155, v147
	v_cvt_f32_ubyte0_e32 v154, v147
	v_pk_mul_f32 v[146:147], v[156:157], v[154:155]
	v_pk_mul_f32 v[150:151], v[158:159], v[150:151]
	v_pk_mul_f32 v[42:43], v[42:43], v[146:147]
	v_pk_mul_f32 v[44:45], v[44:45], v[150:151]
	v_cvt_f32_ubyte0_e32 v0, v152
	v_cvt_f32_ubyte1_e32 v147, v152
	v_cvt_f32_ubyte2_e32 v150, v152
	v_cvt_f32_ubyte3_e32 v151, v152
	v_rcp_iflag_f32_e32 v146, v0
	v_rcp_iflag_f32_e32 v147, v147
	v_rcp_iflag_f32_e32 v150, v150
	v_rcp_iflag_f32_e32 v151, v151
	v_cvt_f32_ubyte0_e32 v152, v153
	v_cvt_f32_ubyte1_e32 v154, v153
	v_cvt_f32_ubyte2_e32 v155, v153
	v_cvt_f32_ubyte3_e32 v156, v153
	v_rcp_iflag_f32_e32 v152, v152
	v_rcp_iflag_f32_e32 v153, v154
	v_rcp_iflag_f32_e32 v154, v155
	v_rcp_iflag_f32_e32 v155, v156
	v_cvt_f32_ubyte3_e32 v157, v148
	v_cvt_f32_ubyte2_e32 v156, v148
	v_cvt_f32_ubyte1_e32 v159, v148
	v_cvt_f32_ubyte0_e32 v158, v148
	v_pk_mul_f32 v[146:147], v[146:147], v[158:159]
	v_pk_mul_f32 v[150:151], v[150:151], v[156:157]
	v_pk_mul_f32 v[38:39], v[38:39], v[146:147]
	v_pk_mul_f32 v[40:41], v[40:41], v[150:151]
	v_cvt_f32_ubyte3_e32 v147, v149
	v_cvt_f32_ubyte2_e32 v146, v149
	v_cvt_f32_ubyte1_e32 v151, v149
	v_cvt_f32_ubyte0_e32 v150, v149
	v_pk_mul_f32 v[148:149], v[152:153], v[150:151]
	v_pk_mul_f32 v[146:147], v[154:155], v[146:147]
	v_pk_mul_f32 v[34:35], v[34:35], v[148:149]
	v_pk_mul_f32 v[36:37], v[36:37], v[146:147]
	s_waitcnt vmcnt(2)
	v_cvt_f32_ubyte0_e32 v0, v142
	v_cvt_f32_ubyte1_e32 v146, v142
	v_cvt_f32_ubyte2_e32 v147, v142
	v_cvt_f32_ubyte3_e32 v148, v142
	v_cvt_f32_ubyte0_e32 v149, v143
	v_cvt_f32_ubyte1_e32 v150, v143
	v_cvt_f32_ubyte2_e32 v151, v143
	v_cvt_f32_ubyte3_e32 v152, v143
	v_rcp_iflag_f32_e32 v142, v0
	v_rcp_iflag_f32_e32 v143, v146
	v_rcp_iflag_f32_e32 v146, v147
	v_rcp_iflag_f32_e32 v147, v148
	v_rcp_iflag_f32_e32 v148, v149
	v_rcp_iflag_f32_e32 v149, v150
	v_rcp_iflag_f32_e32 v150, v151
	v_rcp_iflag_f32_e32 v151, v152
	v_cvt_f32_ubyte3_e32 v153, v138
	v_cvt_f32_ubyte2_e32 v152, v138
	v_cvt_f32_ubyte1_e32 v155, v138
	v_cvt_f32_ubyte0_e32 v154, v138
	v_pk_mul_f32 v[142:143], v[142:143], v[154:155]
	v_pk_mul_f32 v[146:147], v[146:147], v[152:153]
	v_pk_mul_f32 v[30:31], v[30:31], v[142:143]
	v_pk_mul_f32 v[32:33], v[32:33], v[146:147]
	v_cvt_f32_ubyte3_e32 v143, v139
	v_cvt_f32_ubyte2_e32 v142, v139
	v_cvt_f32_ubyte1_e32 v147, v139
	v_cvt_f32_ubyte0_e32 v146, v139
	v_pk_mul_f32 v[138:139], v[148:149], v[146:147]
	v_pk_mul_f32 v[142:143], v[150:151], v[142:143]
	v_pk_mul_f32 v[22:23], v[22:23], v[138:139]
	v_pk_mul_f32 v[24:25], v[24:25], v[142:143]
	v_cvt_f32_ubyte0_e32 v0, v144
	v_cvt_f32_ubyte1_e32 v139, v144
	v_cvt_f32_ubyte2_e32 v142, v144
	v_cvt_f32_ubyte3_e32 v143, v144
	v_rcp_iflag_f32_e32 v138, v0
	v_rcp_iflag_f32_e32 v139, v139
	v_rcp_iflag_f32_e32 v142, v142
	v_rcp_iflag_f32_e32 v143, v143
	v_cvt_f32_ubyte0_e32 v144, v145
	v_cvt_f32_ubyte1_e32 v146, v145
	v_cvt_f32_ubyte2_e32 v147, v145
	v_cvt_f32_ubyte3_e32 v148, v145
	v_rcp_iflag_f32_e32 v144, v144
	v_rcp_iflag_f32_e32 v145, v146
	v_rcp_iflag_f32_e32 v146, v147
	v_rcp_iflag_f32_e32 v147, v148
	v_cvt_f32_ubyte3_e32 v149, v140
	v_cvt_f32_ubyte2_e32 v148, v140
	v_cvt_f32_ubyte1_e32 v151, v140
	v_cvt_f32_ubyte0_e32 v150, v140
	v_pk_mul_f32 v[138:139], v[138:139], v[150:151]
	v_pk_mul_f32 v[142:143], v[142:143], v[148:149]
	v_pk_mul_f32 v[26:27], v[26:27], v[138:139]
	v_pk_mul_f32 v[28:29], v[28:29], v[142:143]
	v_cvt_f32_ubyte3_e32 v139, v141
	v_cvt_f32_ubyte2_e32 v138, v141
	v_cvt_f32_ubyte1_e32 v143, v141
	v_cvt_f32_ubyte0_e32 v142, v141
	v_pk_mul_f32 v[140:141], v[144:145], v[142:143]
	v_pk_mul_f32 v[138:139], v[146:147], v[138:139]
	v_pk_mul_f32 v[18:19], v[18:19], v[140:141]
	v_pk_mul_f32 v[20:21], v[20:21], v[138:139]
	s_waitcnt vmcnt(0)
	v_cvt_f32_ubyte0_e32 v0, v134
	v_cvt_f32_ubyte1_e32 v138, v134
	v_cvt_f32_ubyte2_e32 v139, v134
	v_cvt_f32_ubyte3_e32 v140, v134
	v_cvt_f32_ubyte0_e32 v141, v135
	v_cvt_f32_ubyte1_e32 v142, v135
	v_cvt_f32_ubyte2_e32 v143, v135
	v_cvt_f32_ubyte3_e32 v144, v135
	v_rcp_iflag_f32_e32 v134, v0
	v_rcp_iflag_f32_e32 v135, v138
	v_rcp_iflag_f32_e32 v138, v139
	v_rcp_iflag_f32_e32 v139, v140
	v_rcp_iflag_f32_e32 v140, v141
	v_rcp_iflag_f32_e32 v141, v142
	v_rcp_iflag_f32_e32 v142, v143
	v_rcp_iflag_f32_e32 v143, v144
	v_cvt_f32_ubyte3_e32 v145, v130
	v_cvt_f32_ubyte2_e32 v144, v130
	v_cvt_f32_ubyte1_e32 v147, v130
	v_cvt_f32_ubyte0_e32 v146, v130
	v_pk_mul_f32 v[134:135], v[134:135], v[146:147]
	v_pk_mul_f32 v[138:139], v[138:139], v[144:145]
	v_pk_mul_f32 v[14:15], v[14:15], v[134:135]
	v_pk_mul_f32 v[16:17], v[16:17], v[138:139]
	v_cvt_f32_ubyte3_e32 v135, v131
	v_cvt_f32_ubyte2_e32 v134, v131
	v_cvt_f32_ubyte1_e32 v139, v131
	v_cvt_f32_ubyte0_e32 v138, v131
	v_pk_mul_f32 v[130:131], v[140:141], v[138:139]
	v_pk_mul_f32 v[134:135], v[142:143], v[134:135]
	v_pk_mul_f32 v[6:7], v[6:7], v[130:131]
	v_pk_mul_f32 v[8:9], v[8:9], v[134:135]
	v_cvt_f32_ubyte0_e32 v0, v136
	v_cvt_f32_ubyte1_e32 v131, v136
	v_cvt_f32_ubyte2_e32 v134, v136
	v_cvt_f32_ubyte3_e32 v135, v136
	v_rcp_iflag_f32_e32 v130, v0
	v_rcp_iflag_f32_e32 v131, v131
	v_rcp_iflag_f32_e32 v134, v134
	v_rcp_iflag_f32_e32 v135, v135
	v_cvt_f32_ubyte0_e32 v136, v137
	v_cvt_f32_ubyte1_e32 v138, v137
	v_cvt_f32_ubyte2_e32 v139, v137
	v_cvt_f32_ubyte3_e32 v140, v137
	v_rcp_iflag_f32_e32 v136, v136
	v_rcp_iflag_f32_e32 v137, v138
	v_rcp_iflag_f32_e32 v138, v139
	v_rcp_iflag_f32_e32 v139, v140
	v_cvt_f32_ubyte3_e32 v141, v132
	v_cvt_f32_ubyte2_e32 v140, v132
	v_cvt_f32_ubyte1_e32 v143, v132
	v_cvt_f32_ubyte0_e32 v142, v132
	v_pk_mul_f32 v[130:131], v[130:131], v[142:143]
	v_pk_mul_f32 v[134:135], v[134:135], v[140:141]
	v_pk_mul_f32 v[10:11], v[10:11], v[130:131]
	v_pk_mul_f32 v[12:13], v[12:13], v[134:135]
	v_cvt_f32_ubyte3_e32 v131, v133
	v_cvt_f32_ubyte2_e32 v130, v133
	v_cvt_f32_ubyte1_e32 v135, v133
	v_cvt_f32_ubyte0_e32 v134, v133
	v_pk_mul_f32 v[132:133], v[136:137], v[134:135]
	v_pk_mul_f32 v[130:131], v[138:139], v[130:131]
	v_pk_mul_f32 v[2:3], v[2:3], v[132:133]
	v_pk_mul_f32 v[4:5], v[4:5], v[130:131]

; #define PG8_STAGE(bufoff, gbase, voff) do { _Pragma("unroll") for (int _i = 0; _i < 2; ++_i) \
;         __builtin_amdgcn_global_load_lds((const unsigned*)((const char*)(gbase) + (voff)[_i]), (LAS unsigned*)(lds + (bufoff) + ldsw + _i * 8192), 16, 0, 0); } while (0)
; #define PG8_LDA(dst, b, h) do { _Pragma("unroll") for (int m = 0; m < 4; ++m) _Pragma("unroll") for (int k = 0; k < 2; ++k) dst[m][k] = *(const LAS bf16x8*)(lds + PG8_SA(b, h) + aoffk[k] + m * 2048); } while (0)
; #define PG8_LDB(dst, b, h) do { _Pragma("unroll") for (int n = 0; n < 2; ++n) _Pragma("unroll") for (int k = 0; k < 2; ++k) dst[n][k] = *(const LAS bf16x8*)(lds + PG8_SB(b, h) + boffk[k] + n * 2048); } while (0)
; #define PG8_WAIT_V(n) asm volatile("s_waitcnt vmcnt(" #n ")" ::: "memory")
; #define PG8_WAIT_L(n) asm volatile("s_waitcnt lgkmcnt(" #n ")" ::: "memory")
; #define PG8_BAR __builtin_amdgcn_s_barrier()
; #define PG8_SCHED __builtin_amdgcn_sched_barrier(0)
; template <class Epi, class Sched, class GemmT>
; __device__ __forceinline__ void gemm_phase(LAS unsigned char* lds, const GemmT& g, const Sched& S, const Epi& E, const int wid) {
;     ...
;             for (int t = 0; t < nt; t += 2) {
;                 const bool last = (t == nt - 2);
;                 const char* a1 = cA + (size_t)(t + 1) * kstep;
;                 const char* a2 = last ? ns.A : cA + (size_t)(t + 2) * kstep; const char* b2 = last ? ns.B : cB + (size_t)(t + 2) * kstep;
;                 const char* a3 = a2 + kstep; const char* b3 = b2 + kstep;
;                 unsigned vA2[2], vB2[2];
; #pragma unroll
;                 for (int i = 0; i < 2; ++i) { vA2[i] = last ? nvA[i] : voffA[i]; vB2[i] = last ? nvB[i] : voffB[i]; }
;                 const size_t hA2 = last ? nhA : hstepA, hB2 = last ? nhB : hstepB;
;                 PG8_LDB(B0, 0, 0); PG8_LDB(B1, 0, 1); PG8_SCHED; PG8_LDA(At, 0, 0); PG8_STAGE(PG8_SA(1, 1), a1 + hstepA, voffA);
;                 PG8_WAIT_V(8); PG8_WAIT_L(0); PG8_BAR; PG8_MMA(0, 0, At, B0); PG8_MMA(0, 1, At, B1); PG8_BAR; PG8_SCHED;
;                 PG8_LDA(At, 0, 1); PG8_STAGE(PG8_SB(0, 0), b2, vB2); PG8_STAGE(PG8_SB(0, 1), b2 + hB2, vB2); PG8_STAGE(PG8_SA(0, 0), a2, vA2);
;                 PG8_WAIT_V(8); PG8_WAIT_L(0); PG8_BAR; PG8_MMA(1, 0, At, B0); PG8_MMA(1, 1, At, B1); PG8_BAR; PG8_SCHED;
.LBB0_846:
	ds_read_b128 v[128:131], v194
	ds_read_b128 v[132:135], v195
	ds_read_b128 v[136:139], v196
	ds_read_b128 v[140:143], v197
	ds_read_b128 v[144:147], v198
	ds_read_b128 v[148:151], v199
	ds_read_b128 v[152:155], v200
	ds_read_b128 v[168:171], v201
	s_add_u32 s44, s42, 0xfff00080
	s_addc_u32 s45, s43, -1
	s_cmp_eq_u32 s62, 60
	s_cselect_b32 s51, s37, s45
	s_cselect_b32 s50, s36, s44
	s_cselect_b32 s45, s59, s61
	s_cselect_b32 s44, s41, s60
	v_lshl_add_u64 v[188:189], s[42:43], 0, v[156:157]
	s_add_i32 m0, s14, 0xc000
	ds_read_b128 v[172:175], v202
	ds_read_b128 v[176:179], v202 offset:2048
	ds_read_b128 v[180:183], v203
	ds_read_b128 v[184:187], v203 offset:2048
	ds_read_b128 v[208:211], v202 offset:4096
	ds_read_b128 v[212:215], v202 offset:6144
	ds_read_b128 v[216:219], v203 offset:4096
	ds_read_b128 v[220:223], v203 offset:6144
	global_load_lds_dwordx4 v[188:189], off
	v_lshl_add_u64 v[188:189], s[42:43], 0, v[160:161]
	s_add_i32 m0, s14, 0xe000
	s_nop 0
	global_load_lds_dwordx4 v[188:189], off
	s_waitcnt vmcnt(8)
	s_waitcnt lgkmcnt(0)
	s_barrier
	s_setprio 3
	s_waitcnt lgkmcnt(0)
	v_mfma_f32_16x16x32_bf16 v[76:79], v[132:135], v[220:223], v[76:79]
	v_mfma_f32_16x16x32_bf16 v[76:79], v[128:131], v[212:215], v[76:79]
	v_mfma_f32_16x16x32_bf16 v[124:127], v[128:131], v[172:175], v[124:127]
	v_mfma_f32_16x16x32_bf16 v[124:127], v[132:135], v[180:183], v[124:127]
	v_mfma_f32_16x16x32_bf16 v[108:111], v[132:135], v[184:187], v[108:111]
	v_mfma_f32_16x16x32_bf16 v[108:111], v[128:131], v[176:179], v[108:111]
	v_mfma_f32_16x16x32_bf16 v[92:95], v[128:131], v[208:211], v[92:95]
	v_mfma_f32_16x16x32_bf16 v[92:95], v[132:135], v[216:219], v[92:95]
	v_mfma_f32_16x16x32_bf16 v[88:91], v[140:143], v[216:219], v[88:91]
	v_mfma_f32_16x16x32_bf16 v[88:91], v[136:139], v[208:211], v[88:91]
	v_mfma_f32_16x16x32_bf16 v[120:123], v[136:139], v[172:175], v[120:123]
	v_mfma_f32_16x16x32_bf16 v[120:123], v[140:143], v[180:183], v[120:123]
	v_mfma_f32_16x16x32_bf16 v[104:107], v[140:143], v[184:187], v[104:107]
	v_mfma_f32_16x16x32_bf16 v[104:107], v[136:139], v[176:179], v[104:107]
	v_mfma_f32_16x16x32_bf16 v[72:75], v[136:139], v[212:215], v[72:75]
	v_mfma_f32_16x16x32_bf16 v[72:75], v[140:143], v[220:223], v[72:75]
	s_setprio 0
	s_setprio 3
	v_mfma_f32_16x16x32_bf16 v[68:71], v[148:151], v[220:223], v[68:71]
	v_mfma_f32_16x16x32_bf16 v[68:71], v[144:147], v[212:215], v[68:71]
	v_mfma_f32_16x16x32_bf16 v[116:119], v[144:147], v[172:175], v[116:119]
	v_mfma_f32_16x16x32_bf16 v[116:119], v[148:151], v[180:183], v[116:119]
	v_mfma_f32_16x16x32_bf16 v[100:103], v[148:151], v[184:187], v[100:103]
	v_mfma_f32_16x16x32_bf16 v[100:103], v[144:147], v[176:179], v[100:103]
	v_mfma_f32_16x16x32_bf16 v[84:87], v[144:147], v[208:211], v[84:87]
	v_mfma_f32_16x16x32_bf16 v[84:87], v[148:151], v[216:219], v[84:87]
	v_mfma_f32_16x16x32_bf16 v[80:83], v[168:171], v[216:219], v[80:83]
	v_mfma_f32_16x16x32_bf16 v[80:83], v[152:155], v[208:211], v[80:83]
	v_mfma_f32_16x16x32_bf16 v[112:115], v[152:155], v[172:175], v[112:115]
	v_mfma_f32_16x16x32_bf16 v[112:115], v[168:171], v[180:183], v[112:115]
	v_mfma_f32_16x16x32_bf16 v[96:99], v[168:171], v[184:187], v[96:99]
	v_mfma_f32_16x16x32_bf16 v[96:99], v[152:155], v[176:179], v[96:99]
	v_mfma_f32_16x16x32_bf16 v[64:67], v[152:155], v[212:215], v[64:67]
	v_mfma_f32_16x16x32_bf16 v[64:67], v[168:171], v[220:223], v[64:67]
	s_setprio 0
	s_barrier
	s_add_i32 s48, s54, s68
	v_lshl_add_u64 v[188:189], s[44:45], 0, v[158:159]
	s_mov_b32 m0, s48
	ds_read_b128 v[172:175], v202 offset:16384
	ds_read_b128 v[176:179], v202 offset:18432
	ds_read_b128 v[180:183], v203 offset:16384
	ds_read_b128 v[184:187], v203 offset:18432
	ds_read_b128 v[208:211], v202 offset:20480
	ds_read_b128 v[212:215], v202 offset:22528
	ds_read_b128 v[216:219], v203 offset:20480
	ds_read_b128 v[220:223], v203 offset:22528
	global_load_lds_dwordx4 v[188:189], off
	s_add_i32 m0, s48, 0x2000
	s_add_u32 s48, s44, 0x100000
	v_lshl_add_u64 v[224:225], s[44:45], 0, v[162:163]
	s_addc_u32 s49, s45, 0
	s_add_i32 s63, s55, s68
	global_load_lds_dwordx4 v[224:225], off
	v_lshl_add_u64 v[226:227], s[48:49], 0, v[158:159]
	s_mov_b32 m0, s63
	v_lshl_add_u64 v[230:231], s[50:51], 0, v[160:161]
	global_load_lds_dwordx4 v[226:227], off
	v_lshl_add_u64 v[226:227], s[48:49], 0, v[162:163]
	s_add_i32 m0, s63, 0x2000
	s_nop 0
	global_load_lds_dwordx4 v[226:227], off
	v_lshl_add_u64 v[226:227], s[50:51], 0, v[156:157]
	s_mov_b32 m0, s14
	s_nop 0
	global_load_lds_dwordx4 v[226:227], off
	s_mov_b32 m0, s15
	s_nop 0
	global_load_lds_dwordx4 v[230:231], off
	s_waitcnt vmcnt(8)
	s_waitcnt lgkmcnt(0)
	s_barrier
; #define PG8_STAGE(bufoff, gbase, voff) do { _Pragma("unroll") for (int _i = 0; _i < 2; ++_i) \
;         __builtin_amdgcn_global_load_lds((const unsigned*)((const char*)(gbase) + (voff)[_i]), (LAS unsigned*)(lds + (bufoff) + ldsw + _i * 8192), 16, 0, 0); } while (0)
; #define PG8_LDA(dst, b, h) do { _Pragma("unroll") for (int m = 0; m < 4; ++m) _Pragma("unroll") for (int k = 0; k < 2; ++k) dst[m][k] = *(const LAS bf16x8*)(lds + PG8_SA(b, h) + aoffk[k] + m * 2048); } while (0)
; #define PG8_LDB(dst, b, h) do { _Pragma("unroll") for (int n = 0; n < 2; ++n) _Pragma("unroll") for (int k = 0; k < 2; ++k) dst[n][k] = *(const LAS bf16x8*)(lds + PG8_SB(b, h) + boffk[k] + n * 2048); } while (0)
; #define PG8_WAIT_V(n) asm volatile("s_waitcnt vmcnt(" #n ")" ::: "memory")
; #define PG8_WAIT_L(n) asm volatile("s_waitcnt lgkmcnt(" #n ")" ::: "memory")
; #define PG8_BAR __builtin_amdgcn_s_barrier()
; #define PG8_SCHED __builtin_amdgcn_sched_barrier(0)
; template <class Epi, class Sched, class GemmT>
; __device__ __forceinline__ void gemm_phase(LAS unsigned char* lds, const GemmT& g, const Sched& S, const Epi& E, const int wid) {
;     ...
;                 PG8_WAIT_V(8); PG8_WAIT_L(0); PG8_BAR; PG8_MMA(1, 0, At, B0); PG8_MMA(1, 1, At, B1); PG8_BAR; PG8_SCHED;
;                 PG8_LDB(B0, 1, 0); PG8_LDB(B1, 1, 1); PG8_SCHED; PG8_LDA(At, 1, 0); PG8_STAGE(PG8_SA(0, 1), a2 + hA2, vA2);
;                 PG8_WAIT_V(8); PG8_WAIT_L(0); PG8_BAR; PG8_MMA(0, 0, At, B0); PG8_MMA(0, 1, At, B1); PG8_BAR; PG8_SCHED;
	s_setprio 3
	s_waitcnt lgkmcnt(0)
	v_mfma_f32_16x16x32_bf16 v[4:7], v[132:135], v[220:223], v[4:7]
	v_mfma_f32_16x16x32_bf16 v[4:7], v[128:131], v[212:215], v[4:7]
	v_mfma_f32_16x16x32_bf16 v[52:55], v[128:131], v[172:175], v[52:55]
	v_mfma_f32_16x16x32_bf16 v[52:55], v[132:135], v[180:183], v[52:55]
	v_mfma_f32_16x16x32_bf16 v[36:39], v[132:135], v[184:187], v[36:39]
	v_mfma_f32_16x16x32_bf16 v[36:39], v[128:131], v[176:179], v[36:39]
	v_mfma_f32_16x16x32_bf16 v[20:23], v[128:131], v[208:211], v[20:23]
	v_mfma_f32_16x16x32_bf16 v[20:23], v[132:135], v[216:219], v[20:23]
	v_mfma_f32_16x16x32_bf16 v[16:19], v[140:143], v[216:219], v[16:19]
	v_mfma_f32_16x16x32_bf16 v[16:19], v[136:139], v[208:211], v[16:19]
	v_mfma_f32_16x16x32_bf16 v[48:51], v[136:139], v[172:175], v[48:51]
	v_mfma_f32_16x16x32_bf16 v[48:51], v[140:143], v[180:183], v[48:51]
	v_mfma_f32_16x16x32_bf16 v[32:35], v[140:143], v[184:187], v[32:35]
	v_mfma_f32_16x16x32_bf16 v[32:35], v[136:139], v[176:179], v[32:35]
	v_mfma_f32_16x16x32_bf16 v[0:3], v[136:139], v[212:215], v[0:3]
	v_mfma_f32_16x16x32_bf16 v[0:3], v[140:143], v[220:223], v[0:3]
	s_setprio 0
	s_setprio 3
	v_mfma_f32_16x16x32_bf16 v[12:15], v[148:151], v[220:223], v[12:15]
	v_mfma_f32_16x16x32_bf16 v[12:15], v[144:147], v[212:215], v[12:15]
	v_mfma_f32_16x16x32_bf16 v[60:63], v[144:147], v[172:175], v[60:63]
	v_mfma_f32_16x16x32_bf16 v[60:63], v[148:151], v[180:183], v[60:63]
	v_mfma_f32_16x16x32_bf16 v[44:47], v[148:151], v[184:187], v[44:47]
	v_mfma_f32_16x16x32_bf16 v[44:47], v[144:147], v[176:179], v[44:47]
	v_mfma_f32_16x16x32_bf16 v[28:31], v[144:147], v[208:211], v[28:31]
	v_mfma_f32_16x16x32_bf16 v[28:31], v[148:151], v[216:219], v[28:31]
	v_mfma_f32_16x16x32_bf16 v[24:27], v[168:171], v[216:219], v[24:27]
	v_mfma_f32_16x16x32_bf16 v[24:27], v[152:155], v[208:211], v[24:27]
	v_mfma_f32_16x16x32_bf16 v[56:59], v[152:155], v[172:175], v[56:59]
	v_mfma_f32_16x16x32_bf16 v[56:59], v[168:171], v[180:183], v[56:59]
	v_mfma_f32_16x16x32_bf16 v[40:43], v[168:171], v[184:187], v[40:43]
	v_mfma_f32_16x16x32_bf16 v[40:43], v[152:155], v[176:179], v[40:43]
	v_mfma_f32_16x16x32_bf16 v[8:11], v[152:155], v[212:215], v[8:11]
	v_mfma_f32_16x16x32_bf16 v[8:11], v[168:171], v[220:223], v[8:11]
	s_setprio 0
	s_barrier
	s_add_i32 s63, 0, 0x18000
	s_add_i32 s64, 0, 0x1c000
	v_add_u32_e32 v128, s63, v191
	v_add_u32_e32 v132, s63, v192
	v_add_u32_e32 v144, s64, v191
	v_add_u32_e32 v148, s64, v192
	ds_read_b128 v[128:131], v128
	ds_read_b128 v[132:135], v132
	ds_read_b128 v[136:139], v204
	ds_read_b128 v[140:143], v205
	ds_read_b128 v[144:147], v144
	ds_read_b128 v[148:151], v148
	ds_read_b128 v[152:155], v206
	ds_read_b128 v[168:171], v207
	s_add_u32 s48, s50, 0x100000
	s_addc_u32 s49, s51, 0
	s_mov_b32 m0, s22
	v_lshl_add_u64 v[232:233], s[48:49], 0, v[156:157]
	ds_read_b128 v[172:175], v202 offset:32768
	ds_read_b128 v[176:179], v202 offset:34816
	ds_read_b128 v[180:183], v203 offset:32768
	ds_read_b128 v[184:187], v203 offset:34816
	ds_read_b128 v[208:211], v202 offset:36864
	ds_read_b128 v[212:215], v202 offset:38912
	ds_read_b128 v[216:219], v203 offset:36864
	ds_read_b128 v[220:223], v203 offset:38912
	global_load_lds_dwordx4 v[232:233], off
	v_lshl_add_u64 v[232:233], s[48:49], 0, v[160:161]
	s_mov_b32 m0, s23
	s_nop 0
	global_load_lds_dwordx4 v[232:233], off
	s_waitcnt vmcnt(8)
	s_waitcnt lgkmcnt(0)
	s_barrier
	s_setprio 3
	s_waitcnt lgkmcnt(0)
	v_mfma_f32_16x16x32_bf16 v[76:79], v[132:135], v[220:223], v[76:79]
	v_mfma_f32_16x16x32_bf16 v[76:79], v[128:131], v[212:215], v[76:79]
	v_mfma_f32_16x16x32_bf16 v[124:127], v[128:131], v[172:175], v[124:127]
	v_mfma_f32_16x16x32_bf16 v[124:127], v[132:135], v[180:183], v[124:127]
	v_mfma_f32_16x16x32_bf16 v[108:111], v[132:135], v[184:187], v[108:111]
	v_mfma_f32_16x16x32_bf16 v[108:111], v[128:131], v[176:179], v[108:111]
	v_mfma_f32_16x16x32_bf16 v[92:95], v[128:131], v[208:211], v[92:95]
	v_mfma_f32_16x16x32_bf16 v[92:95], v[132:135], v[216:219], v[92:95]
	v_mfma_f32_16x16x32_bf16 v[88:91], v[140:143], v[216:219], v[88:91]
	v_mfma_f32_16x16x32_bf16 v[88:91], v[136:139], v[208:211], v[88:91]
	v_mfma_f32_16x16x32_bf16 v[120:123], v[136:139], v[172:175], v[120:123]
	v_mfma_f32_16x16x32_bf16 v[120:123], v[140:143], v[180:183], v[120:123]
	v_mfma_f32_16x16x32_bf16 v[104:107], v[140:143], v[184:187], v[104:107]
	v_mfma_f32_16x16x32_bf16 v[104:107], v[136:139], v[176:179], v[104:107]
	v_mfma_f32_16x16x32_bf16 v[72:75], v[136:139], v[212:215], v[72:75]
	v_mfma_f32_16x16x32_bf16 v[72:75], v[140:143], v[220:223], v[72:75]
	s_setprio 0
	s_setprio 3
	v_mfma_f32_16x16x32_bf16 v[68:71], v[148:151], v[220:223], v[68:71]
	v_mfma_f32_16x16x32_bf16 v[68:71], v[144:147], v[212:215], v[68:71]
	v_mfma_f32_16x16x32_bf16 v[116:119], v[144:147], v[172:175], v[116:119]
	v_mfma_f32_16x16x32_bf16 v[116:119], v[148:151], v[180:183], v[116:119]
	v_mfma_f32_16x16x32_bf16 v[100:103], v[148:151], v[184:187], v[100:103]
	v_mfma_f32_16x16x32_bf16 v[100:103], v[144:147], v[176:179], v[100:103]
	v_mfma_f32_16x16x32_bf16 v[84:87], v[144:147], v[208:211], v[84:87]
	v_mfma_f32_16x16x32_bf16 v[84:87], v[148:151], v[216:219], v[84:87]
	v_mfma_f32_16x16x32_bf16 v[80:83], v[168:171], v[216:219], v[80:83]
	v_mfma_f32_16x16x32_bf16 v[80:83], v[152:155], v[208:211], v[80:83]
	v_mfma_f32_16x16x32_bf16 v[112:115], v[152:155], v[172:175], v[112:115]
	v_mfma_f32_16x16x32_bf16 v[112:115], v[168:171], v[180:183], v[112:115]
	v_mfma_f32_16x16x32_bf16 v[96:99], v[168:171], v[184:187], v[96:99]
	v_mfma_f32_16x16x32_bf16 v[96:99], v[152:155], v[176:179], v[96:99]
	v_mfma_f32_16x16x32_bf16 v[64:67], v[152:155], v[212:215], v[64:67]
	v_mfma_f32_16x16x32_bf16 v[64:67], v[168:171], v[220:223], v[64:67]
	s_setprio 0
	s_barrier
; #define PG8_STAGE(bufoff, gbase, voff) do { _Pragma("unroll") for (int _i = 0; _i < 2; ++_i) \
;         __builtin_amdgcn_global_load_lds((const unsigned*)((const char*)(gbase) + (voff)[_i]), (LAS unsigned*)(lds + (bufoff) + ldsw + _i * 8192), 16, 0, 0); } while (0)
; #define PG8_LDA(dst, b, h) do { _Pragma("unroll") for (int m = 0; m < 4; ++m) _Pragma("unroll") for (int k = 0; k < 2; ++k) dst[m][k] = *(const LAS bf16x8*)(lds + PG8_SA(b, h) + aoffk[k] + m * 2048); } while (0)
; #define PG8_WAIT_V(n) asm volatile("s_waitcnt vmcnt(" #n ")" ::: "memory")
; #define PG8_WAIT_L(n) asm volatile("s_waitcnt lgkmcnt(" #n ")" ::: "memory")
; #define PG8_BAR __builtin_amdgcn_s_barrier()
; #define PG8_SCHED __builtin_amdgcn_sched_barrier(0)
; template <class Epi, class Sched, class GemmT>
; __device__ __forceinline__ void gemm_phase(LAS unsigned char* lds, const GemmT& g, const Sched& S, const Epi& E, const int wid) {
;     ...
;                 PG8_LDA(At, 1, 1); PG8_STAGE(PG8_SB(1, 0), b3, vB2); PG8_STAGE(PG8_SB(1, 1), b3 + hB2, vB2); PG8_STAGE(PG8_SA(1, 0), a3, vA2);
;                 PG8_WAIT_V(8); PG8_WAIT_L(0); PG8_BAR; PG8_MMA(1, 0, At, B0); PG8_MMA(1, 1, At, B1); PG8_BAR; PG8_SCHED;
;             }
;             if constexpr (NSEG > 1) { if (sgi + 1 < NSEG) E.mid(acc, cur, sgi, wr, wc, fr, fq); }
;             cs = ns; cA = ns.A; cB = ns.B; hstepA = nhA; hstepB = nhB;
; #pragma unroll
;             for (int i = 0; i < 2; ++i) { voffA[i] = nvA[i]; voffB[i] = nvB[i]; }
;         }
;         if (wr == 0) PG8_BAR;
	s_add_i32 s48, s63, s68
	v_lshl_add_u64 v[188:189], v[188:189], 0, s[18:19]
	s_mov_b32 m0, s48
	ds_read_b128 v[172:175], v202 offset:49152
	ds_read_b128 v[176:179], v202 offset:51200
	ds_read_b128 v[180:183], v203 offset:49152
	ds_read_b128 v[184:187], v203 offset:51200
	ds_read_b128 v[208:211], v202 offset:53248
	ds_read_b128 v[212:215], v202 offset:55296
	ds_read_b128 v[216:219], v203 offset:53248
	ds_read_b128 v[220:223], v203 offset:55296
	global_load_lds_dwordx4 v[188:189], off
	s_add_i32 m0, s48, 0x2000
	s_add_u32 s44, s44, 0x100080
	v_lshl_add_u64 v[188:189], v[224:225], 0, s[18:19]
	s_addc_u32 s45, s45, 0
	s_add_i32 s48, s64, s68
	global_load_lds_dwordx4 v[188:189], off
	v_lshl_add_u64 v[188:189], s[44:45], 0, v[158:159]
	s_mov_b32 m0, s48
	s_nop 0
	global_load_lds_dwordx4 v[188:189], off
	v_lshl_add_u64 v[188:189], s[44:45], 0, v[162:163]
	s_add_i32 m0, s48, 0x2000
	s_nop 0
	global_load_lds_dwordx4 v[188:189], off
	v_lshl_add_u64 v[188:189], v[226:227], 0, s[18:19]
	s_mov_b32 m0, s34
	s_nop 0
	global_load_lds_dwordx4 v[188:189], off
	v_lshl_add_u64 v[188:189], v[230:231], 0, s[18:19]
	s_mov_b32 m0, s35
	s_nop 0
	global_load_lds_dwordx4 v[188:189], off
	s_waitcnt vmcnt(8)
	s_waitcnt lgkmcnt(0)
	s_barrier
	s_setprio 3
	s_waitcnt lgkmcnt(0)
	v_mfma_f32_16x16x32_bf16 v[4:7], v[132:135], v[220:223], v[4:7]
	v_mfma_f32_16x16x32_bf16 v[4:7], v[128:131], v[212:215], v[4:7]
	v_mfma_f32_16x16x32_bf16 v[52:55], v[128:131], v[172:175], v[52:55]
	v_mfma_f32_16x16x32_bf16 v[52:55], v[132:135], v[180:183], v[52:55]
	v_mfma_f32_16x16x32_bf16 v[36:39], v[132:135], v[184:187], v[36:39]
	v_mfma_f32_16x16x32_bf16 v[36:39], v[128:131], v[176:179], v[36:39]
	v_mfma_f32_16x16x32_bf16 v[20:23], v[128:131], v[208:211], v[20:23]
	v_mfma_f32_16x16x32_bf16 v[20:23], v[132:135], v[216:219], v[20:23]
	v_mfma_f32_16x16x32_bf16 v[16:19], v[140:143], v[216:219], v[16:19]
	v_mfma_f32_16x16x32_bf16 v[16:19], v[136:139], v[208:211], v[16:19]
	v_mfma_f32_16x16x32_bf16 v[48:51], v[136:139], v[172:175], v[48:51]
	v_mfma_f32_16x16x32_bf16 v[48:51], v[140:143], v[180:183], v[48:51]
	v_mfma_f32_16x16x32_bf16 v[32:35], v[140:143], v[184:187], v[32:35]
	v_mfma_f32_16x16x32_bf16 v[32:35], v[136:139], v[176:179], v[32:35]
	v_mfma_f32_16x16x32_bf16 v[0:3], v[136:139], v[212:215], v[0:3]
	v_mfma_f32_16x16x32_bf16 v[0:3], v[140:143], v[220:223], v[0:3]
	s_setprio 0
	s_setprio 3
	v_mfma_f32_16x16x32_bf16 v[12:15], v[148:151], v[220:223], v[12:15]
	v_mfma_f32_16x16x32_bf16 v[12:15], v[144:147], v[212:215], v[12:15]
	v_mfma_f32_16x16x32_bf16 v[60:63], v[144:147], v[172:175], v[60:63]
	v_mfma_f32_16x16x32_bf16 v[60:63], v[148:151], v[180:183], v[60:63]
	v_mfma_f32_16x16x32_bf16 v[44:47], v[148:151], v[184:187], v[44:47]
	v_mfma_f32_16x16x32_bf16 v[44:47], v[144:147], v[176:179], v[44:47]
	v_mfma_f32_16x16x32_bf16 v[28:31], v[144:147], v[208:211], v[28:31]
	v_mfma_f32_16x16x32_bf16 v[28:31], v[148:151], v[216:219], v[28:31]
	v_mfma_f32_16x16x32_bf16 v[24:27], v[168:171], v[216:219], v[24:27]
	v_mfma_f32_16x16x32_bf16 v[24:27], v[152:155], v[208:211], v[24:27]
	v_mfma_f32_16x16x32_bf16 v[56:59], v[152:155], v[172:175], v[56:59]
	v_mfma_f32_16x16x32_bf16 v[56:59], v[168:171], v[180:183], v[56:59]
	v_mfma_f32_16x16x32_bf16 v[40:43], v[168:171], v[184:187], v[40:43]
	v_mfma_f32_16x16x32_bf16 v[40:43], v[152:155], v[176:179], v[40:43]
	v_mfma_f32_16x16x32_bf16 v[8:11], v[152:155], v[212:215], v[8:11]
	v_mfma_f32_16x16x32_bf16 v[8:11], v[168:171], v[220:223], v[8:11]
	s_setprio 0
	s_barrier
	s_add_i32 s62, s62, 2
	s_add_u32 s42, s42, 0x100
	s_addc_u32 s43, s43, 0
	s_add_u32 s60, s60, 0x100
	s_addc_u32 s61, s61, 0
	s_cmp_gt_u32 s62, 61
	s_cbranch_scc0 .LBB0_846
	s_and_b64 vcc, exec, s[20:21]
	s_cbranch_vccz .LBB0_849
	s_barrier

; #define PG8_STAGE(bufoff, gbase, voff) do { _Pragma("unroll") for (int _i = 0; _i < 2; ++_i) \
;         __builtin_amdgcn_global_load_lds((const unsigned*)((const char*)(gbase) + (voff)[_i]), (LAS unsigned*)(lds + (bufoff) + ldsw + _i * 8192), 16, 0, 0); } while (0)
; #define PG8_LDA(dst, b, h) do { _Pragma("unroll") for (int m = 0; m < 4; ++m) _Pragma("unroll") for (int k = 0; k < 2; ++k) dst[m][k] = *(const LAS bf16x8*)(lds + PG8_SA(b, h) + aoffk[k] + m * 2048); } while (0)
; #define PG8_LDB(dst, b, h) do { _Pragma("unroll") for (int n = 0; n < 2; ++n) _Pragma("unroll") for (int k = 0; k < 2; ++k) dst[n][k] = *(const LAS bf16x8*)(lds + PG8_SB(b, h) + boffk[k] + n * 2048); } while (0)
; #define PG8_WAIT_V(n) asm volatile("s_waitcnt vmcnt(" #n ")" ::: "memory")
; #define PG8_WAIT_L(n) asm volatile("s_waitcnt lgkmcnt(" #n ")" ::: "memory")
; #define PG8_BAR __builtin_amdgcn_s_barrier()
; #define PG8_SCHED __builtin_amdgcn_sched_barrier(0)
; template <class Epi, class Sched, class GemmT>
; __device__ __forceinline__ void gemm_phase(LAS unsigned char* lds, const GemmT& g, const Sched& S, const Epi& E, const int wid) {
;     ...
;             for (int t = 0; t < nt; t += 2) {
;                 const bool last = (t == nt - 2);
;                 const char* a1 = cA + (size_t)(t + 1) * kstep;
;                 const char* a2 = last ? ns.A : cA + (size_t)(t + 2) * kstep; const char* b2 = last ? ns.B : cB + (size_t)(t + 2) * kstep;
;                 const char* a3 = a2 + kstep; const char* b3 = b2 + kstep;
;                 unsigned vA2[2], vB2[2];
; #pragma unroll
;                 for (int i = 0; i < 2; ++i) { vA2[i] = last ? nvA[i] : voffA[i]; vB2[i] = last ? nvB[i] : voffB[i]; }
;                 const size_t hA2 = last ? nhA : hstepA, hB2 = last ? nhB : hstepB;
;                 PG8_LDB(B0, 0, 0); PG8_LDB(B1, 0, 1); PG8_SCHED; PG8_LDA(At, 0, 0); PG8_STAGE(PG8_SA(1, 1), a1 + hstepA, voffA);
;                 PG8_WAIT_V(8); PG8_WAIT_L(0); PG8_BAR; PG8_MMA(0, 0, At, B0); PG8_MMA(0, 1, At, B1); PG8_BAR; PG8_SCHED;
;                 PG8_LDA(At, 0, 1); PG8_STAGE(PG8_SB(0, 0), b2, vB2); PG8_STAGE(PG8_SB(0, 1), b2 + hB2, vB2); PG8_STAGE(PG8_SA(0, 0), a2, vA2);
;                 PG8_WAIT_V(8); PG8_WAIT_L(0); PG8_BAR; PG8_MMA(1, 0, At, B0); PG8_MMA(1, 1, At, B1); PG8_BAR; PG8_SCHED;
.LBB0_936:
	ds_read_b128 v[12:15], v223
	ds_read_b128 v[132:135], v224
	ds_read_b128 v[136:139], v225
	ds_read_b128 v[140:143], v226
	ds_read_b128 v[144:147], v227
	ds_read_b128 v[148:151], v229
	ds_read_b128 v[152:155], v230
	ds_read_b128 v[156:159], v231
	s_add_u32 s66, s64, 0xfff00080
	s_addc_u32 s67, s65, -1
	s_cmp_eq_u32 s81, 60
	s_cselect_b32 s71, s57, s67
	s_cselect_b32 s70, s56, s66
	s_cselect_b32 s67, s77, s79
	s_cselect_b32 s66, s63, s78
	v_lshl_add_u64 v[204:205], s[64:65], 0, v[176:177]
	s_add_i32 m0, s14, 0xc000
	ds_read_b128 v[160:163], v232
	ds_read_b128 v[164:167], v232 offset:2048
	ds_read_b128 v[168:171], v233
	ds_read_b128 v[172:175], v233 offset:2048
	ds_read_b128 v[188:191], v232 offset:4096
	ds_read_b128 v[192:195], v232 offset:6144
	ds_read_b128 v[196:199], v233 offset:4096
	ds_read_b128 v[200:203], v233 offset:6144
	global_load_lds_dwordx4 v[204:205], off
	v_lshl_add_u64 v[204:205], s[64:65], 0, v[180:181]
	s_add_i32 m0, s14, 0xe000
	s_nop 0
	global_load_lds_dwordx4 v[204:205], off
	s_waitcnt vmcnt(8)
	s_waitcnt lgkmcnt(0)
	s_barrier
	s_setprio 3
	s_waitcnt lgkmcnt(0)
	v_mfma_f32_16x16x32_bf16 v[124:127], v[12:15], v[160:163], v[124:127]
	v_mfma_f32_16x16x32_bf16 v[124:127], v[132:135], v[168:171], v[124:127]
	v_mfma_f32_16x16x32_bf16 v[40:43], v[132:135], v[172:175], v[40:43]
	v_mfma_f32_16x16x32_bf16 v[40:43], v[12:15], v[164:167], v[40:43]
	v_mfma_f32_16x16x32_bf16 v[32:35], v[12:15], v[188:191], v[32:35]
	v_mfma_f32_16x16x32_bf16 v[32:35], v[132:135], v[196:199], v[32:35]
	v_mfma_f32_16x16x32_bf16 v[112:115], v[132:135], v[200:203], v[112:115]
	v_mfma_f32_16x16x32_bf16 v[112:115], v[12:15], v[192:195], v[112:115]
	v_mfma_f32_16x16x32_bf16 v[92:95], v[136:139], v[192:195], v[92:95]
	v_mfma_f32_16x16x32_bf16 v[92:95], v[140:143], v[200:203], v[92:95]
	v_mfma_f32_16x16x32_bf16 v[120:123], v[140:143], v[168:171], v[120:123]
	v_mfma_f32_16x16x32_bf16 v[120:123], v[136:139], v[160:163], v[120:123]
	v_mfma_f32_16x16x32_bf16 v[104:107], v[136:139], v[164:167], v[104:107]
	v_mfma_f32_16x16x32_bf16 v[104:107], v[140:143], v[172:175], v[104:107]
	v_mfma_f32_16x16x32_bf16 v[96:99], v[140:143], v[196:199], v[96:99]
	v_mfma_f32_16x16x32_bf16 v[96:99], v[136:139], v[188:191], v[96:99]
	s_setprio 0
	s_setprio 3
	v_mfma_f32_16x16x32_bf16 v[72:75], v[144:147], v[188:191], v[72:75]
	v_mfma_f32_16x16x32_bf16 v[72:75], v[148:151], v[196:199], v[72:75]
	v_mfma_f32_16x16x32_bf16 v[68:71], v[148:151], v[168:171], v[68:71]
	v_mfma_f32_16x16x32_bf16 v[68:71], v[144:147], v[160:163], v[68:71]
	v_mfma_f32_16x16x32_bf16 v[76:79], v[144:147], v[164:167], v[76:79]
	v_mfma_f32_16x16x32_bf16 v[76:79], v[148:151], v[172:175], v[76:79]
	v_mfma_f32_16x16x32_bf16 v[84:87], v[148:151], v[200:203], v[84:87]
	v_mfma_f32_16x16x32_bf16 v[84:87], v[144:147], v[192:195], v[84:87]
	v_mfma_f32_16x16x32_bf16 v[80:83], v[152:155], v[192:195], v[80:83]
	v_mfma_f32_16x16x32_bf16 v[80:83], v[156:159], v[200:203], v[80:83]
	v_mfma_f32_16x16x32_bf16 v[60:63], v[156:159], v[168:171], v[60:63]
	v_mfma_f32_16x16x32_bf16 v[60:63], v[152:155], v[160:163], v[60:63]
	v_mfma_f32_16x16x32_bf16 v[20:23], v[152:155], v[164:167], v[20:23]
	v_mfma_f32_16x16x32_bf16 v[20:23], v[156:159], v[172:175], v[20:23]
	v_mfma_f32_16x16x32_bf16 v[16:19], v[156:159], v[196:199], v[16:19]
	v_mfma_f32_16x16x32_bf16 v[16:19], v[152:155], v[188:191], v[16:19]
	s_setprio 0
	s_barrier
	s_add_i32 s80, s69, s68
	v_lshl_add_u64 v[204:205], s[66:67], 0, v[178:179]
	s_mov_b32 m0, s80
	ds_read_b128 v[160:163], v232 offset:16384
	ds_read_b128 v[164:167], v232 offset:18432
	ds_read_b128 v[168:171], v233 offset:16384
	ds_read_b128 v[172:175], v233 offset:18432
	ds_read_b128 v[188:191], v232 offset:20480
	ds_read_b128 v[192:195], v232 offset:22528
	ds_read_b128 v[196:199], v233 offset:20480
	ds_read_b128 v[200:203], v233 offset:22528
	global_load_lds_dwordx4 v[204:205], off
	s_add_i32 m0, s80, 0x2000
	s_add_u32 s82, s66, 0x100000
	v_lshl_add_u64 v[206:207], s[66:67], 0, v[182:183]
	s_addc_u32 s83, s67, 0
	s_add_i32 s80, s72, s68
	global_load_lds_dwordx4 v[206:207], off
	v_lshl_add_u64 v[240:241], s[82:83], 0, v[178:179]
	s_mov_b32 m0, s80
	v_lshl_add_u64 v[242:243], s[70:71], 0, v[180:181]
	global_load_lds_dwordx4 v[240:241], off
	v_lshl_add_u64 v[240:241], s[82:83], 0, v[182:183]
	s_add_i32 m0, s80, 0x2000
	s_nop 0
	global_load_lds_dwordx4 v[240:241], off
	v_lshl_add_u64 v[240:241], s[70:71], 0, v[176:177]
	s_mov_b32 m0, s14
	s_nop 0
	global_load_lds_dwordx4 v[240:241], off
	s_mov_b32 m0, s15
	s_nop 0
	global_load_lds_dwordx4 v[242:243], off
	s_waitcnt vmcnt(8)
	s_waitcnt lgkmcnt(0)
	s_barrier
; #define PG8_STAGE(bufoff, gbase, voff) do { _Pragma("unroll") for (int _i = 0; _i < 2; ++_i) \
;         __builtin_amdgcn_global_load_lds((const unsigned*)((const char*)(gbase) + (voff)[_i]), (LAS unsigned*)(lds + (bufoff) + ldsw + _i * 8192), 16, 0, 0); } while (0)
; #define PG8_LDA(dst, b, h) do { _Pragma("unroll") for (int m = 0; m < 4; ++m) _Pragma("unroll") for (int k = 0; k < 2; ++k) dst[m][k] = *(const LAS bf16x8*)(lds + PG8_SA(b, h) + aoffk[k] + m * 2048); } while (0)
; #define PG8_LDB(dst, b, h) do { _Pragma("unroll") for (int n = 0; n < 2; ++n) _Pragma("unroll") for (int k = 0; k < 2; ++k) dst[n][k] = *(const LAS bf16x8*)(lds + PG8_SB(b, h) + boffk[k] + n * 2048); } while (0)
; #define PG8_WAIT_V(n) asm volatile("s_waitcnt vmcnt(" #n ")" ::: "memory")
; #define PG8_WAIT_L(n) asm volatile("s_waitcnt lgkmcnt(" #n ")" ::: "memory")
; #define PG8_BAR __builtin_amdgcn_s_barrier()
; #define PG8_SCHED __builtin_amdgcn_sched_barrier(0)
; template <class Epi, class Sched, class GemmT>
; __device__ __forceinline__ void gemm_phase(LAS unsigned char* lds, const GemmT& g, const Sched& S, const Epi& E, const int wid) {
;     ...
;                 PG8_WAIT_V(8); PG8_WAIT_L(0); PG8_BAR; PG8_MMA(1, 0, At, B0); PG8_MMA(1, 1, At, B1); PG8_BAR; PG8_SCHED;
;                 PG8_LDB(B0, 1, 0); PG8_LDB(B1, 1, 1); PG8_SCHED; PG8_LDA(At, 1, 0); PG8_STAGE(PG8_SA(0, 1), a2 + hA2, vA2);
;                 PG8_WAIT_V(8); PG8_WAIT_L(0); PG8_BAR; PG8_MMA(0, 0, At, B0); PG8_MMA(0, 1, At, B1); PG8_BAR; PG8_SCHED;
	s_setprio 3
	s_waitcnt lgkmcnt(0)
	v_mfma_f32_16x16x32_bf16 v[56:59], v[12:15], v[160:163], v[56:59]
	v_mfma_f32_16x16x32_bf16 v[56:59], v[132:135], v[168:171], v[56:59]
	v_mfma_f32_16x16x32_bf16 v[108:111], v[136:139], v[160:163], v[108:111]
	v_mfma_f32_16x16x32_bf16 v[108:111], v[140:143], v[168:171], v[108:111]
	v_mfma_f32_16x16x32_bf16 v[36:39], v[12:15], v[164:167], v[36:39]
	v_mfma_f32_16x16x32_bf16 v[36:39], v[132:135], v[172:175], v[36:39]
	v_mfma_f32_16x16x32_bf16 v[100:103], v[136:139], v[164:167], v[100:103]
	v_mfma_f32_16x16x32_bf16 v[100:103], v[140:143], v[172:175], v[100:103]
	v_mfma_f32_16x16x32_bf16 v[28:31], v[12:15], v[188:191], v[28:31]
	v_mfma_f32_16x16x32_bf16 v[28:31], v[132:135], v[196:199], v[28:31]
	v_mfma_f32_16x16x32_bf16 v[88:91], v[136:139], v[188:191], v[88:91]
	v_mfma_f32_16x16x32_bf16 v[88:91], v[140:143], v[196:199], v[88:91]
	v_mfma_f32_16x16x32_bf16 v[24:27], v[136:139], v[192:195], v[24:27]
	v_mfma_f32_16x16x32_bf16 v[24:27], v[140:143], v[200:203], v[24:27]
	v_mfma_f32_16x16x32_bf16 v[12:15], v[12:15], v[192:195], v[64:67]
	v_mfma_f32_16x16x32_bf16 v[12:15], v[132:135], v[200:203], v[12:15]
	s_setprio 0
	s_setprio 3
	v_mfma_f32_16x16x32_bf16 v[64:67], v[144:147], v[192:195], v[116:119]
	v_mfma_f32_16x16x32_bf16 v[116:119], v[148:151], v[200:203], v[64:67]
	v_mfma_f32_16x16x32_bf16 v[44:47], v[144:147], v[160:163], v[44:47]
	v_mfma_f32_16x16x32_bf16 v[44:47], v[148:151], v[168:171], v[44:47]
	v_mfma_f32_16x16x32_bf16 v[0:3], v[152:155], v[160:163], v[0:3]
	v_mfma_f32_16x16x32_bf16 v[0:3], v[156:159], v[168:171], v[0:3]
	v_mfma_f32_16x16x32_bf16 v[48:51], v[144:147], v[164:167], v[48:51]
	v_mfma_f32_16x16x32_bf16 v[48:51], v[148:151], v[172:175], v[48:51]
	v_mfma_f32_16x16x32_bf16 v[4:7], v[152:155], v[164:167], v[4:7]
	v_mfma_f32_16x16x32_bf16 v[4:7], v[156:159], v[172:175], v[4:7]
	v_mfma_f32_16x16x32_bf16 v[64:67], v[152:155], v[192:195], v[128:131]
	v_mfma_f32_16x16x32_bf16 v[128:131], v[156:159], v[200:203], v[64:67]
	v_mfma_f32_16x16x32_bf16 v[52:55], v[144:147], v[188:191], v[52:55]
	v_mfma_f32_16x16x32_bf16 v[52:55], v[148:151], v[196:199], v[52:55]
	v_mfma_f32_16x16x32_bf16 v[8:11], v[152:155], v[188:191], v[8:11]
	v_mfma_f32_16x16x32_bf16 v[8:11], v[156:159], v[196:199], v[8:11]
	s_setprio 0
	s_barrier
	s_add_i32 s80, 0, 0x18000
	s_add_i32 s82, 0, 0x1c000
	v_add_u32_e32 v64, s80, v210
	v_add_u32_e32 v132, s80, v211
	v_add_u32_e32 v144, s82, v210
	v_add_u32_e32 v148, s82, v211
	ds_read_b128 v[64:67], v64
	ds_read_b128 v[132:135], v132
	ds_read_b128 v[136:139], v234
	ds_read_b128 v[140:143], v235
	ds_read_b128 v[144:147], v144
	ds_read_b128 v[148:151], v148
	ds_read_b128 v[152:155], v236
	ds_read_b128 v[156:159], v237
	s_add_u32 s70, s70, 0x100000
	s_addc_u32 s71, s71, 0
	s_mov_b32 m0, s23
	v_lshl_add_u64 v[244:245], s[70:71], 0, v[176:177]
	ds_read_b128 v[160:163], v232 offset:32768
	ds_read_b128 v[164:167], v232 offset:34816
	ds_read_b128 v[168:171], v233 offset:32768
	ds_read_b128 v[172:175], v233 offset:34816
	ds_read_b128 v[188:191], v232 offset:36864
	ds_read_b128 v[192:195], v232 offset:38912
	ds_read_b128 v[196:199], v233 offset:36864
	ds_read_b128 v[200:203], v233 offset:38912
	global_load_lds_dwordx4 v[244:245], off
	v_lshl_add_u64 v[244:245], s[70:71], 0, v[180:181]
	s_mov_b32 m0, s34
	s_nop 0
	global_load_lds_dwordx4 v[244:245], off
	s_waitcnt vmcnt(8)
	s_waitcnt lgkmcnt(0)
	s_barrier
	s_setprio 3
	s_waitcnt lgkmcnt(0)
	v_mfma_f32_16x16x32_bf16 v[124:127], v[64:67], v[160:163], v[124:127]
	v_mfma_f32_16x16x32_bf16 v[124:127], v[132:135], v[168:171], v[124:127]
	v_mfma_f32_16x16x32_bf16 v[40:43], v[132:135], v[172:175], v[40:43]
	v_mfma_f32_16x16x32_bf16 v[40:43], v[64:67], v[164:167], v[40:43]
	v_mfma_f32_16x16x32_bf16 v[32:35], v[64:67], v[188:191], v[32:35]
	v_mfma_f32_16x16x32_bf16 v[32:35], v[132:135], v[196:199], v[32:35]
	v_mfma_f32_16x16x32_bf16 v[112:115], v[132:135], v[200:203], v[112:115]
	v_mfma_f32_16x16x32_bf16 v[112:115], v[64:67], v[192:195], v[112:115]
	v_mfma_f32_16x16x32_bf16 v[92:95], v[136:139], v[192:195], v[92:95]
	v_mfma_f32_16x16x32_bf16 v[92:95], v[140:143], v[200:203], v[92:95]
	v_mfma_f32_16x16x32_bf16 v[120:123], v[140:143], v[168:171], v[120:123]
	v_mfma_f32_16x16x32_bf16 v[120:123], v[136:139], v[160:163], v[120:123]
	v_mfma_f32_16x16x32_bf16 v[104:107], v[136:139], v[164:167], v[104:107]
	v_mfma_f32_16x16x32_bf16 v[104:107], v[140:143], v[172:175], v[104:107]
	v_mfma_f32_16x16x32_bf16 v[96:99], v[140:143], v[196:199], v[96:99]
	v_mfma_f32_16x16x32_bf16 v[96:99], v[136:139], v[188:191], v[96:99]
	s_setprio 0
	s_setprio 3
	v_mfma_f32_16x16x32_bf16 v[72:75], v[144:147], v[188:191], v[72:75]
	v_mfma_f32_16x16x32_bf16 v[72:75], v[148:151], v[196:199], v[72:75]
	v_mfma_f32_16x16x32_bf16 v[68:71], v[148:151], v[168:171], v[68:71]
	v_mfma_f32_16x16x32_bf16 v[68:71], v[144:147], v[160:163], v[68:71]
	v_mfma_f32_16x16x32_bf16 v[76:79], v[144:147], v[164:167], v[76:79]
	v_mfma_f32_16x16x32_bf16 v[76:79], v[148:151], v[172:175], v[76:79]
	v_mfma_f32_16x16x32_bf16 v[84:87], v[148:151], v[200:203], v[84:87]
	v_mfma_f32_16x16x32_bf16 v[84:87], v[144:147], v[192:195], v[84:87]
	v_mfma_f32_16x16x32_bf16 v[80:83], v[152:155], v[192:195], v[80:83]
	v_mfma_f32_16x16x32_bf16 v[80:83], v[156:159], v[200:203], v[80:83]
	v_mfma_f32_16x16x32_bf16 v[60:63], v[156:159], v[168:171], v[60:63]
	v_mfma_f32_16x16x32_bf16 v[60:63], v[152:155], v[160:163], v[60:63]
	v_mfma_f32_16x16x32_bf16 v[20:23], v[152:155], v[164:167], v[20:23]
	v_mfma_f32_16x16x32_bf16 v[20:23], v[156:159], v[172:175], v[20:23]
	v_mfma_f32_16x16x32_bf16 v[16:19], v[156:159], v[196:199], v[16:19]
	v_mfma_f32_16x16x32_bf16 v[16:19], v[152:155], v[188:191], v[16:19]
	s_setprio 0
	s_barrier
; #define PG8_STAGE(bufoff, gbase, voff) do { _Pragma("unroll") for (int _i = 0; _i < 2; ++_i) \
;         __builtin_amdgcn_global_load_lds((const unsigned*)((const char*)(gbase) + (voff)[_i]), (LAS unsigned*)(lds + (bufoff) + ldsw + _i * 8192), 16, 0, 0); } while (0)
; #define PG8_LDA(dst, b, h) do { _Pragma("unroll") for (int m = 0; m < 4; ++m) _Pragma("unroll") for (int k = 0; k < 2; ++k) dst[m][k] = *(const LAS bf16x8*)(lds + PG8_SA(b, h) + aoffk[k] + m * 2048); } while (0)
; #define PG8_WAIT_V(n) asm volatile("s_waitcnt vmcnt(" #n ")" ::: "memory")
; #define PG8_WAIT_L(n) asm volatile("s_waitcnt lgkmcnt(" #n ")" ::: "memory")
; #define PG8_BAR __builtin_amdgcn_s_barrier()
; #define PG8_SCHED __builtin_amdgcn_sched_barrier(0)
; template <class Epi, class Sched, class GemmT>
; __device__ __forceinline__ void gemm_phase(LAS unsigned char* lds, const GemmT& g, const Sched& S, const Epi& E, const int wid) {
;     ...
;                 PG8_LDA(At, 1, 1); PG8_STAGE(PG8_SB(1, 0), b3, vB2); PG8_STAGE(PG8_SB(1, 1), b3 + hB2, vB2); PG8_STAGE(PG8_SA(1, 0), a3, vA2);
;                 PG8_WAIT_V(8); PG8_WAIT_L(0); PG8_BAR; PG8_MMA(1, 0, At, B0); PG8_MMA(1, 1, At, B1); PG8_BAR; PG8_SCHED;
;             }
;             if constexpr (NSEG > 1) { if (sgi + 1 < NSEG) E.mid(acc, cur, sgi, wr, wc, fr, fq); }
;             cs = ns; cA = ns.A; cB = ns.B; hstepA = nhA; hstepB = nhB;
; #pragma unroll
;             for (int i = 0; i < 2; ++i) { voffA[i] = nvA[i]; voffB[i] = nvB[i]; }
;         }
;         if (wr == 0) PG8_BAR;
	s_add_i32 s70, s80, s68
	v_lshl_add_u64 v[204:205], v[204:205], 0, s[38:39]
	s_mov_b32 m0, s70
	ds_read_b128 v[160:163], v232 offset:49152
	ds_read_b128 v[164:167], v232 offset:51200
	ds_read_b128 v[168:171], v233 offset:49152
	ds_read_b128 v[172:175], v233 offset:51200
	ds_read_b128 v[188:191], v232 offset:53248
	ds_read_b128 v[192:195], v232 offset:55296
	ds_read_b128 v[196:199], v233 offset:53248
	ds_read_b128 v[200:203], v233 offset:55296
	global_load_lds_dwordx4 v[204:205], off
	s_add_i32 m0, s70, 0x2000
	s_add_u32 s66, s66, 0x100080
	v_lshl_add_u64 v[204:205], v[206:207], 0, s[38:39]
	s_addc_u32 s67, s67, 0
	s_add_i32 s70, s82, s68
	global_load_lds_dwordx4 v[204:205], off
	v_lshl_add_u64 v[204:205], s[66:67], 0, v[178:179]
	s_mov_b32 m0, s70
	s_nop 0
	global_load_lds_dwordx4 v[204:205], off
	v_lshl_add_u64 v[204:205], s[66:67], 0, v[182:183]
	s_add_i32 m0, s70, 0x2000
	s_nop 0
	global_load_lds_dwordx4 v[204:205], off
	v_lshl_add_u64 v[204:205], v[240:241], 0, s[38:39]
	s_mov_b32 m0, s54
	s_nop 0
	global_load_lds_dwordx4 v[204:205], off
	v_lshl_add_u64 v[204:205], v[242:243], 0, s[38:39]
	s_mov_b32 m0, s55
	s_nop 0
	global_load_lds_dwordx4 v[204:205], off
	s_waitcnt vmcnt(8)
	s_waitcnt lgkmcnt(0)
	s_barrier
	s_setprio 3
	s_waitcnt lgkmcnt(0)
	v_mfma_f32_16x16x32_bf16 v[12:15], v[64:67], v[192:195], v[12:15]
	v_mfma_f32_16x16x32_bf16 v[56:59], v[64:67], v[160:163], v[56:59]
	v_mfma_f32_16x16x32_bf16 v[56:59], v[132:135], v[168:171], v[56:59]
	v_mfma_f32_16x16x32_bf16 v[108:111], v[136:139], v[160:163], v[108:111]
	v_mfma_f32_16x16x32_bf16 v[108:111], v[140:143], v[168:171], v[108:111]
	v_mfma_f32_16x16x32_bf16 v[36:39], v[64:67], v[164:167], v[36:39]
	v_mfma_f32_16x16x32_bf16 v[36:39], v[132:135], v[172:175], v[36:39]
	v_mfma_f32_16x16x32_bf16 v[100:103], v[136:139], v[164:167], v[100:103]
	v_mfma_f32_16x16x32_bf16 v[100:103], v[140:143], v[172:175], v[100:103]
	v_mfma_f32_16x16x32_bf16 v[28:31], v[64:67], v[188:191], v[28:31]
	v_mfma_f32_16x16x32_bf16 v[28:31], v[132:135], v[196:199], v[28:31]
	v_mfma_f32_16x16x32_bf16 v[88:91], v[136:139], v[188:191], v[88:91]
	v_mfma_f32_16x16x32_bf16 v[88:91], v[140:143], v[196:199], v[88:91]
	v_mfma_f32_16x16x32_bf16 v[64:67], v[132:135], v[200:203], v[12:15]
	v_mfma_f32_16x16x32_bf16 v[12:15], v[136:139], v[192:195], v[24:27]
	v_mfma_f32_16x16x32_bf16 v[24:27], v[140:143], v[200:203], v[12:15]
	s_setprio 0
	s_setprio 3
	v_mfma_f32_16x16x32_bf16 v[12:15], v[144:147], v[160:163], v[44:47]
	v_mfma_f32_16x16x32_bf16 v[44:47], v[148:151], v[168:171], v[12:15]
	v_mfma_f32_16x16x32_bf16 v[0:3], v[152:155], v[160:163], v[0:3]
	v_mfma_f32_16x16x32_bf16 v[0:3], v[156:159], v[168:171], v[0:3]
	v_mfma_f32_16x16x32_bf16 v[4:7], v[152:155], v[164:167], v[4:7]
	v_mfma_f32_16x16x32_bf16 v[4:7], v[156:159], v[172:175], v[4:7]
	v_mfma_f32_16x16x32_bf16 v[12:15], v[144:147], v[164:167], v[48:51]
	v_mfma_f32_16x16x32_bf16 v[48:51], v[148:151], v[172:175], v[12:15]
	v_mfma_f32_16x16x32_bf16 v[8:11], v[152:155], v[188:191], v[8:11]
	v_mfma_f32_16x16x32_bf16 v[8:11], v[156:159], v[196:199], v[8:11]
	v_mfma_f32_16x16x32_bf16 v[12:15], v[144:147], v[188:191], v[52:55]
	v_mfma_f32_16x16x32_bf16 v[52:55], v[148:151], v[196:199], v[12:15]
	v_mfma_f32_16x16x32_bf16 v[12:15], v[144:147], v[192:195], v[116:119]
	v_mfma_f32_16x16x32_bf16 v[116:119], v[148:151], v[200:203], v[12:15]
	v_mfma_f32_16x16x32_bf16 v[12:15], v[152:155], v[192:195], v[128:131]
	v_mfma_f32_16x16x32_bf16 v[128:131], v[156:159], v[200:203], v[12:15]
	s_setprio 0
	s_barrier
	s_add_i32 s81, s81, 2
	s_add_u32 s64, s64, 0x100
	s_addc_u32 s65, s65, 0
	s_add_u32 s78, s78, 0x100
	s_addc_u32 s79, s79, 0
	s_cmp_gt_u32 s81, 61
	s_cbranch_scc0 .LBB0_936
	s_and_b64 vcc, exec, s[40:41]
	s_cbranch_vccz .LBB0_939
	s_barrier

; #define PG8_STAGE(bufoff, gbase, voff) do { _Pragma("unroll") for (int _i = 0; _i < 2; ++_i) \
;         __builtin_amdgcn_global_load_lds((const unsigned*)((const char*)(gbase) + (voff)[_i]), (LAS unsigned*)(lds + (bufoff) + ldsw + _i * 8192), 16, 0, 0); } while (0)
; #define PG8_LDA(dst, b, h) do { _Pragma("unroll") for (int m = 0; m < 4; ++m) _Pragma("unroll") for (int k = 0; k < 2; ++k) dst[m][k] = *(const LAS bf16x8*)(lds + PG8_SA(b, h) + aoffk[k] + m * 2048); } while (0)
; #define PG8_LDB(dst, b, h) do { _Pragma("unroll") for (int n = 0; n < 2; ++n) _Pragma("unroll") for (int k = 0; k < 2; ++k) dst[n][k] = *(const LAS bf16x8*)(lds + PG8_SB(b, h) + boffk[k] + n * 2048); } while (0)
; #define PG8_WAIT_V(n) asm volatile("s_waitcnt vmcnt(" #n ")" ::: "memory")
; #define PG8_WAIT_L(n) asm volatile("s_waitcnt lgkmcnt(" #n ")" ::: "memory")
; #define PG8_BAR __builtin_amdgcn_s_barrier()
; #define PG8_SCHED __builtin_amdgcn_sched_barrier(0)
; template <class Epi, class Sched, class GemmT>
; __device__ __forceinline__ void gemm_phase(LAS unsigned char* lds, const GemmT& g, const Sched& S, const Epi& E, const int wid) {
;     ...
;             for (int t = 0; t < nt; t += 2) {
;                 const bool last = (t == nt - 2);
;                 const char* a1 = cA + (size_t)(t + 1) * kstep;
;                 const char* a2 = last ? ns.A : cA + (size_t)(t + 2) * kstep; const char* b2 = last ? ns.B : cB + (size_t)(t + 2) * kstep;
;                 const char* a3 = a2 + kstep; const char* b3 = b2 + kstep;
;                 unsigned vA2[2], vB2[2];
; #pragma unroll
;                 for (int i = 0; i < 2; ++i) { vA2[i] = last ? nvA[i] : voffA[i]; vB2[i] = last ? nvB[i] : voffB[i]; }
;                 const size_t hA2 = last ? nhA : hstepA, hB2 = last ? nhB : hstepB;
;                 PG8_LDB(B0, 0, 0); PG8_LDB(B1, 0, 1); PG8_SCHED; PG8_LDA(At, 0, 0); PG8_STAGE(PG8_SA(1, 1), a1 + hstepA, voffA);
;                 PG8_WAIT_V(8); PG8_WAIT_L(0); PG8_BAR; PG8_MMA(0, 0, At, B0); PG8_MMA(0, 1, At, B1); PG8_BAR; PG8_SCHED;
;                 PG8_LDA(At, 0, 1); PG8_STAGE(PG8_SB(0, 0), b2, vB2); PG8_STAGE(PG8_SB(0, 1), b2 + hB2, vB2); PG8_STAGE(PG8_SA(0, 0), a2, vA2);
;                 PG8_WAIT_V(8); PG8_WAIT_L(0); PG8_BAR; PG8_MMA(1, 0, At, B0); PG8_MMA(1, 1, At, B1); PG8_BAR; PG8_SCHED;
.LBB0_1096:
	ds_read_b128 v[128:131], v188
	ds_read_b128 v[132:135], v189
	ds_read_b128 v[136:139], v190
	ds_read_b128 v[140:143], v191
	ds_read_b128 v[144:147], v192
	ds_read_b128 v[148:151], v193
	ds_read_b128 v[152:155], v194
	ds_read_b128 v[156:159], v195
	s_add_u32 s24, s22, 0xffd50080
	s_addc_u32 s25, s23, -1
	s_cmpk_eq_i32 s56, 0xa8
	s_cselect_b32 s27, s19, s25
	s_cselect_b32 s26, s18, s24
	s_cselect_b32 s25, s53, s55
	s_cselect_b32 s24, s52, s54
	v_lshl_add_u64 v[222:223], s[22:23], 0, v[168:169]
	s_add_i32 m0, s34, 0xc000
	ds_read_b128 v[160:163], v196
	ds_read_b128 v[164:167], v196 offset:2048
	ds_read_b128 v[180:183], v197
	ds_read_b128 v[202:205], v197 offset:2048
	ds_read_b128 v[206:209], v196 offset:4096
	ds_read_b128 v[210:213], v196 offset:6144
	ds_read_b128 v[214:217], v197 offset:4096
	ds_read_b128 v[218:221], v197 offset:6144
	global_load_lds_dwordx4 v[222:223], off
	v_lshl_add_u64 v[222:223], s[22:23], 0, v[172:173]
	s_add_i32 m0, s34, 0xe000
	s_nop 0
	global_load_lds_dwordx4 v[222:223], off
	s_waitcnt vmcnt(8)
	s_waitcnt lgkmcnt(0)
	s_barrier
	s_setprio 3
	s_waitcnt lgkmcnt(0)
	v_mfma_f32_16x16x32_bf16 v[124:127], v[128:131], v[160:163], v[124:127]
	v_mfma_f32_16x16x32_bf16 v[124:127], v[132:135], v[180:183], v[124:127]
	v_mfma_f32_16x16x32_bf16 v[112:115], v[132:135], v[202:205], v[112:115]
	v_mfma_f32_16x16x32_bf16 v[112:115], v[128:131], v[164:167], v[112:115]
	v_mfma_f32_16x16x32_bf16 v[96:99], v[128:131], v[206:209], v[96:99]
	v_mfma_f32_16x16x32_bf16 v[96:99], v[132:135], v[214:217], v[96:99]
	v_mfma_f32_16x16x32_bf16 v[80:83], v[132:135], v[218:221], v[80:83]
	v_mfma_f32_16x16x32_bf16 v[80:83], v[128:131], v[210:213], v[80:83]
	v_mfma_f32_16x16x32_bf16 v[72:75], v[136:139], v[210:213], v[72:75]
	v_mfma_f32_16x16x32_bf16 v[72:75], v[140:143], v[218:221], v[72:75]
	v_mfma_f32_16x16x32_bf16 v[120:123], v[140:143], v[180:183], v[120:123]
	v_mfma_f32_16x16x32_bf16 v[120:123], v[136:139], v[160:163], v[120:123]
	v_mfma_f32_16x16x32_bf16 v[104:107], v[136:139], v[164:167], v[104:107]
	v_mfma_f32_16x16x32_bf16 v[104:107], v[140:143], v[202:205], v[104:107]
	v_mfma_f32_16x16x32_bf16 v[88:91], v[140:143], v[214:217], v[88:91]
	v_mfma_f32_16x16x32_bf16 v[88:91], v[136:139], v[206:209], v[88:91]
	s_setprio 0
	s_setprio 3
	v_mfma_f32_16x16x32_bf16 v[84:87], v[144:147], v[206:209], v[84:87]
	v_mfma_f32_16x16x32_bf16 v[84:87], v[148:151], v[214:217], v[84:87]
	v_mfma_f32_16x16x32_bf16 v[116:119], v[148:151], v[180:183], v[116:119]
	v_mfma_f32_16x16x32_bf16 v[116:119], v[144:147], v[160:163], v[116:119]
	v_mfma_f32_16x16x32_bf16 v[100:103], v[144:147], v[164:167], v[100:103]
	v_mfma_f32_16x16x32_bf16 v[100:103], v[148:151], v[202:205], v[100:103]
	v_mfma_f32_16x16x32_bf16 v[68:71], v[148:151], v[218:221], v[68:71]
	v_mfma_f32_16x16x32_bf16 v[68:71], v[144:147], v[210:213], v[68:71]
	v_mfma_f32_16x16x32_bf16 v[60:63], v[152:155], v[210:213], v[60:63]
	v_mfma_f32_16x16x32_bf16 v[60:63], v[156:159], v[218:221], v[60:63]
	v_mfma_f32_16x16x32_bf16 v[108:111], v[156:159], v[180:183], v[108:111]
	v_mfma_f32_16x16x32_bf16 v[108:111], v[152:155], v[160:163], v[108:111]
	v_mfma_f32_16x16x32_bf16 v[92:95], v[152:155], v[164:167], v[92:95]
	v_mfma_f32_16x16x32_bf16 v[92:95], v[156:159], v[202:205], v[92:95]
	v_mfma_f32_16x16x32_bf16 v[76:79], v[156:159], v[214:217], v[76:79]
	v_mfma_f32_16x16x32_bf16 v[76:79], v[152:155], v[206:209], v[76:79]
	s_setprio 0
	s_barrier
	s_add_i32 s57, s41, s68
	v_lshl_add_u64 v[222:223], s[24:25], 0, v[170:171]
	s_mov_b32 m0, s57
	ds_read_b128 v[160:163], v196 offset:16384
	ds_read_b128 v[164:167], v196 offset:18432
	ds_read_b128 v[180:183], v197 offset:16384
	ds_read_b128 v[202:205], v197 offset:18432
	ds_read_b128 v[206:209], v196 offset:20480
	ds_read_b128 v[210:213], v196 offset:22528
	ds_read_b128 v[214:217], v197 offset:20480
	ds_read_b128 v[218:221], v197 offset:22528
	global_load_lds_dwordx4 v[222:223], off
	s_add_i32 m0, s57, 0x2000
	s_add_u32 s58, s24, 0x2b0000
	v_lshl_add_u64 v[224:225], s[24:25], 0, v[174:175]
	s_addc_u32 s59, s25, 0
	s_add_i32 s57, s42, s68
	global_load_lds_dwordx4 v[224:225], off
	v_lshl_add_u64 v[226:227], s[58:59], 0, v[170:171]
	s_mov_b32 m0, s57
	v_lshl_add_u64 v[228:229], s[26:27], 0, v[172:173]
	global_load_lds_dwordx4 v[226:227], off
	v_lshl_add_u64 v[226:227], s[58:59], 0, v[174:175]
	s_add_i32 m0, s57, 0x2000
	s_nop 0
	global_load_lds_dwordx4 v[226:227], off
	v_lshl_add_u64 v[226:227], s[26:27], 0, v[168:169]
	s_mov_b32 m0, s34
	s_nop 0
	global_load_lds_dwordx4 v[226:227], off
	s_mov_b32 m0, s35
	s_nop 0
	global_load_lds_dwordx4 v[228:229], off
	s_waitcnt vmcnt(8)
	s_waitcnt lgkmcnt(0)
	s_barrier
; #define PG8_STAGE(bufoff, gbase, voff) do { _Pragma("unroll") for (int _i = 0; _i < 2; ++_i) \
;         __builtin_amdgcn_global_load_lds((const unsigned*)((const char*)(gbase) + (voff)[_i]), (LAS unsigned*)(lds + (bufoff) + ldsw + _i * 8192), 16, 0, 0); } while (0)
; #define PG8_LDA(dst, b, h) do { _Pragma("unroll") for (int m = 0; m < 4; ++m) _Pragma("unroll") for (int k = 0; k < 2; ++k) dst[m][k] = *(const LAS bf16x8*)(lds + PG8_SA(b, h) + aoffk[k] + m * 2048); } while (0)
; #define PG8_LDB(dst, b, h) do { _Pragma("unroll") for (int n = 0; n < 2; ++n) _Pragma("unroll") for (int k = 0; k < 2; ++k) dst[n][k] = *(const LAS bf16x8*)(lds + PG8_SB(b, h) + boffk[k] + n * 2048); } while (0)
; #define PG8_WAIT_V(n) asm volatile("s_waitcnt vmcnt(" #n ")" ::: "memory")
; #define PG8_WAIT_L(n) asm volatile("s_waitcnt lgkmcnt(" #n ")" ::: "memory")
; #define PG8_BAR __builtin_amdgcn_s_barrier()
; #define PG8_SCHED __builtin_amdgcn_sched_barrier(0)
; template <class Epi, class Sched, class GemmT>
; __device__ __forceinline__ void gemm_phase(LAS unsigned char* lds, const GemmT& g, const Sched& S, const Epi& E, const int wid) {
;     ...
;                 PG8_WAIT_V(8); PG8_WAIT_L(0); PG8_BAR; PG8_MMA(1, 0, At, B0); PG8_MMA(1, 1, At, B1); PG8_BAR; PG8_SCHED;
;                 PG8_LDB(B0, 1, 0); PG8_LDB(B1, 1, 1); PG8_SCHED; PG8_LDA(At, 1, 0); PG8_STAGE(PG8_SA(0, 1), a2 + hA2, vA2);
;                 PG8_WAIT_V(8); PG8_WAIT_L(0); PG8_BAR; PG8_MMA(0, 0, At, B0); PG8_MMA(0, 1, At, B1); PG8_BAR; PG8_SCHED;
	s_setprio 3
	s_waitcnt lgkmcnt(0)
	v_mfma_f32_16x16x32_bf16 v[20:23], v[128:131], v[206:209], v[20:23]
	v_mfma_f32_16x16x32_bf16 v[20:23], v[132:135], v[214:217], v[20:23]
	v_mfma_f32_16x16x32_bf16 v[52:55], v[132:135], v[180:183], v[52:55]
	v_mfma_f32_16x16x32_bf16 v[52:55], v[128:131], v[160:163], v[52:55]
	v_mfma_f32_16x16x32_bf16 v[36:39], v[128:131], v[164:167], v[36:39]
	v_mfma_f32_16x16x32_bf16 v[36:39], v[132:135], v[202:205], v[36:39]
	v_mfma_f32_16x16x32_bf16 v[4:7], v[132:135], v[218:221], v[4:7]
	v_mfma_f32_16x16x32_bf16 v[4:7], v[128:131], v[210:213], v[4:7]
	v_mfma_f32_16x16x32_bf16 v[0:3], v[136:139], v[210:213], v[0:3]
	v_mfma_f32_16x16x32_bf16 v[0:3], v[140:143], v[218:221], v[0:3]
	v_mfma_f32_16x16x32_bf16 v[48:51], v[140:143], v[180:183], v[48:51]
	v_mfma_f32_16x16x32_bf16 v[48:51], v[136:139], v[160:163], v[48:51]
	v_mfma_f32_16x16x32_bf16 v[32:35], v[136:139], v[164:167], v[32:35]
	v_mfma_f32_16x16x32_bf16 v[32:35], v[140:143], v[202:205], v[32:35]
	v_mfma_f32_16x16x32_bf16 v[8:11], v[140:143], v[214:217], v[8:11]
	v_mfma_f32_16x16x32_bf16 v[8:11], v[136:139], v[206:209], v[8:11]
	s_setprio 0
	s_setprio 3
	v_mfma_f32_16x16x32_bf16 v[28:31], v[144:147], v[206:209], v[28:31]
	v_mfma_f32_16x16x32_bf16 v[28:31], v[148:151], v[214:217], v[28:31]
	v_mfma_f32_16x16x32_bf16 v[64:67], v[148:151], v[180:183], v[64:67]
	v_mfma_f32_16x16x32_bf16 v[64:67], v[144:147], v[160:163], v[64:67]
	v_mfma_f32_16x16x32_bf16 v[44:47], v[144:147], v[164:167], v[44:47]
	v_mfma_f32_16x16x32_bf16 v[44:47], v[148:151], v[202:205], v[44:47]
	v_mfma_f32_16x16x32_bf16 v[16:19], v[148:151], v[218:221], v[16:19]
	v_mfma_f32_16x16x32_bf16 v[16:19], v[144:147], v[210:213], v[16:19]
	v_mfma_f32_16x16x32_bf16 v[12:15], v[152:155], v[210:213], v[12:15]
	v_mfma_f32_16x16x32_bf16 v[12:15], v[156:159], v[218:221], v[12:15]
	v_mfma_f32_16x16x32_bf16 v[56:59], v[156:159], v[180:183], v[56:59]
	v_mfma_f32_16x16x32_bf16 v[56:59], v[152:155], v[160:163], v[56:59]
	v_mfma_f32_16x16x32_bf16 v[40:43], v[152:155], v[164:167], v[40:43]
	v_mfma_f32_16x16x32_bf16 v[40:43], v[156:159], v[202:205], v[40:43]
	v_mfma_f32_16x16x32_bf16 v[24:27], v[156:159], v[214:217], v[24:27]
	v_mfma_f32_16x16x32_bf16 v[24:27], v[152:155], v[206:209], v[24:27]
	s_setprio 0
	s_barrier
	s_add_i32 s57, 0, 0x18000
	s_add_i32 s58, 0, 0x1c000
	v_add_u32_e32 v128, s57, v185
	v_add_u32_e32 v132, s57, v186
	v_add_u32_e32 v144, s58, v185
	v_add_u32_e32 v148, s58, v186
	ds_read_b128 v[128:131], v128
	ds_read_b128 v[132:135], v132
	ds_read_b128 v[136:139], v198
	ds_read_b128 v[140:143], v199
	ds_read_b128 v[144:147], v144
	ds_read_b128 v[148:151], v148
	ds_read_b128 v[152:155], v200
	ds_read_b128 v[156:159], v201
	s_add_u32 s26, s26, 0x2b0000
	s_addc_u32 s27, s27, 0
	s_mov_b32 m0, s36
	v_lshl_add_u64 v[230:231], s[26:27], 0, v[168:169]
	ds_read_b128 v[160:163], v196 offset:32768
	ds_read_b128 v[164:167], v196 offset:34816
	ds_read_b128 v[180:183], v197 offset:32768
	ds_read_b128 v[202:205], v197 offset:34816
	ds_read_b128 v[206:209], v196 offset:36864
	ds_read_b128 v[210:213], v196 offset:38912
	ds_read_b128 v[214:217], v197 offset:36864
	ds_read_b128 v[218:221], v197 offset:38912
	global_load_lds_dwordx4 v[230:231], off
	v_lshl_add_u64 v[230:231], s[26:27], 0, v[172:173]
	s_mov_b32 m0, s37
	s_nop 0
	global_load_lds_dwordx4 v[230:231], off
	s_waitcnt vmcnt(8)
	s_waitcnt lgkmcnt(0)
	s_barrier
	s_setprio 3
	s_waitcnt lgkmcnt(0)
	v_mfma_f32_16x16x32_bf16 v[96:99], v[128:131], v[206:209], v[96:99]
	v_mfma_f32_16x16x32_bf16 v[96:99], v[132:135], v[214:217], v[96:99]
	v_mfma_f32_16x16x32_bf16 v[124:127], v[132:135], v[180:183], v[124:127]
	v_mfma_f32_16x16x32_bf16 v[124:127], v[128:131], v[160:163], v[124:127]
	v_mfma_f32_16x16x32_bf16 v[112:115], v[128:131], v[164:167], v[112:115]
	v_mfma_f32_16x16x32_bf16 v[112:115], v[132:135], v[202:205], v[112:115]
	v_mfma_f32_16x16x32_bf16 v[80:83], v[132:135], v[218:221], v[80:83]
	v_mfma_f32_16x16x32_bf16 v[80:83], v[128:131], v[210:213], v[80:83]
	v_mfma_f32_16x16x32_bf16 v[72:75], v[136:139], v[210:213], v[72:75]
	v_mfma_f32_16x16x32_bf16 v[72:75], v[140:143], v[218:221], v[72:75]
	v_mfma_f32_16x16x32_bf16 v[120:123], v[140:143], v[180:183], v[120:123]
	v_mfma_f32_16x16x32_bf16 v[120:123], v[136:139], v[160:163], v[120:123]
	v_mfma_f32_16x16x32_bf16 v[104:107], v[136:139], v[164:167], v[104:107]
	v_mfma_f32_16x16x32_bf16 v[104:107], v[140:143], v[202:205], v[104:107]
	v_mfma_f32_16x16x32_bf16 v[88:91], v[140:143], v[214:217], v[88:91]
	v_mfma_f32_16x16x32_bf16 v[88:91], v[136:139], v[206:209], v[88:91]
	s_setprio 0
	s_setprio 3
	v_mfma_f32_16x16x32_bf16 v[84:87], v[144:147], v[206:209], v[84:87]
	v_mfma_f32_16x16x32_bf16 v[84:87], v[148:151], v[214:217], v[84:87]
	v_mfma_f32_16x16x32_bf16 v[116:119], v[148:151], v[180:183], v[116:119]
	v_mfma_f32_16x16x32_bf16 v[116:119], v[144:147], v[160:163], v[116:119]
	v_mfma_f32_16x16x32_bf16 v[100:103], v[144:147], v[164:167], v[100:103]
	v_mfma_f32_16x16x32_bf16 v[100:103], v[148:151], v[202:205], v[100:103]
	v_mfma_f32_16x16x32_bf16 v[68:71], v[148:151], v[218:221], v[68:71]
	v_mfma_f32_16x16x32_bf16 v[68:71], v[144:147], v[210:213], v[68:71]
	v_mfma_f32_16x16x32_bf16 v[60:63], v[152:155], v[210:213], v[60:63]
	v_mfma_f32_16x16x32_bf16 v[60:63], v[156:159], v[218:221], v[60:63]
	v_mfma_f32_16x16x32_bf16 v[108:111], v[156:159], v[180:183], v[108:111]
	v_mfma_f32_16x16x32_bf16 v[108:111], v[152:155], v[160:163], v[108:111]
	v_mfma_f32_16x16x32_bf16 v[92:95], v[152:155], v[164:167], v[92:95]
	v_mfma_f32_16x16x32_bf16 v[92:95], v[156:159], v[202:205], v[92:95]
	v_mfma_f32_16x16x32_bf16 v[76:79], v[156:159], v[214:217], v[76:79]
	v_mfma_f32_16x16x32_bf16 v[76:79], v[152:155], v[206:209], v[76:79]
	s_setprio 0
	s_barrier
; #define PG8_STAGE(bufoff, gbase, voff) do { _Pragma("unroll") for (int _i = 0; _i < 2; ++_i) \
;         __builtin_amdgcn_global_load_lds((const unsigned*)((const char*)(gbase) + (voff)[_i]), (LAS unsigned*)(lds + (bufoff) + ldsw + _i * 8192), 16, 0, 0); } while (0)
; #define PG8_LDA(dst, b, h) do { _Pragma("unroll") for (int m = 0; m < 4; ++m) _Pragma("unroll") for (int k = 0; k < 2; ++k) dst[m][k] = *(const LAS bf16x8*)(lds + PG8_SA(b, h) + aoffk[k] + m * 2048); } while (0)
; #define PG8_WAIT_V(n) asm volatile("s_waitcnt vmcnt(" #n ")" ::: "memory")
; #define PG8_WAIT_L(n) asm volatile("s_waitcnt lgkmcnt(" #n ")" ::: "memory")
; #define PG8_BAR __builtin_amdgcn_s_barrier()
; #define PG8_SCHED __builtin_amdgcn_sched_barrier(0)
; template <class Epi, class Sched, class GemmT>
; __device__ __forceinline__ void gemm_phase(LAS unsigned char* lds, const GemmT& g, const Sched& S, const Epi& E, const int wid) {
;     ...
;                 PG8_LDA(At, 1, 1); PG8_STAGE(PG8_SB(1, 0), b3, vB2); PG8_STAGE(PG8_SB(1, 1), b3 + hB2, vB2); PG8_STAGE(PG8_SA(1, 0), a3, vA2);
;                 PG8_WAIT_V(8); PG8_WAIT_L(0); PG8_BAR; PG8_MMA(1, 0, At, B0); PG8_MMA(1, 1, At, B1); PG8_BAR; PG8_SCHED;
;             }
;             if constexpr (NSEG > 1) { if (sgi + 1 < NSEG) E.mid(acc, cur, sgi, wr, wc, fr, fq); }
;             cs = ns; cA = ns.A; cB = ns.B; hstepA = nhA; hstepB = nhB;
; #pragma unroll
;             for (int i = 0; i < 2; ++i) { voffA[i] = nvA[i]; voffB[i] = nvB[i]; }
;         }
;         if (wr == 0) PG8_BAR;
	s_add_i32 s26, s57, s68
	v_lshl_add_u64 v[222:223], v[222:223], 0, s[6:7]
	s_mov_b32 m0, s26
	ds_read_b128 v[160:163], v196 offset:49152
	ds_read_b128 v[164:167], v196 offset:51200
	ds_read_b128 v[180:183], v197 offset:49152
	ds_read_b128 v[202:205], v197 offset:51200
	ds_read_b128 v[206:209], v196 offset:53248
	ds_read_b128 v[210:213], v196 offset:55296
	ds_read_b128 v[214:217], v197 offset:53248
	ds_read_b128 v[218:221], v197 offset:55296
	global_load_lds_dwordx4 v[222:223], off
	s_add_i32 m0, s26, 0x2000
	s_add_u32 s24, s24, 0x2b0080
	v_lshl_add_u64 v[222:223], v[224:225], 0, s[6:7]
	s_addc_u32 s25, s25, 0
	s_add_i32 s26, s58, s68
	global_load_lds_dwordx4 v[222:223], off
	v_lshl_add_u64 v[222:223], s[24:25], 0, v[170:171]
	s_mov_b32 m0, s26
	s_nop 0
	global_load_lds_dwordx4 v[222:223], off
	v_lshl_add_u64 v[222:223], s[24:25], 0, v[174:175]
	s_add_i32 m0, s26, 0x2000
	s_nop 0
	global_load_lds_dwordx4 v[222:223], off
	v_lshl_add_u64 v[222:223], v[226:227], 0, s[6:7]
	s_mov_b32 m0, s39
	s_nop 0
	global_load_lds_dwordx4 v[222:223], off
	v_lshl_add_u64 v[222:223], v[228:229], 0, s[6:7]
	s_mov_b32 m0, s40
	s_nop 0
	global_load_lds_dwordx4 v[222:223], off
	s_waitcnt vmcnt(8)
	s_waitcnt lgkmcnt(0)
	s_barrier
	s_setprio 3
	s_waitcnt lgkmcnt(0)
	v_mfma_f32_16x16x32_bf16 v[20:23], v[128:131], v[206:209], v[20:23]
	v_mfma_f32_16x16x32_bf16 v[20:23], v[132:135], v[214:217], v[20:23]
	v_mfma_f32_16x16x32_bf16 v[52:55], v[132:135], v[180:183], v[52:55]
	v_mfma_f32_16x16x32_bf16 v[52:55], v[128:131], v[160:163], v[52:55]
	v_mfma_f32_16x16x32_bf16 v[36:39], v[128:131], v[164:167], v[36:39]
	v_mfma_f32_16x16x32_bf16 v[36:39], v[132:135], v[202:205], v[36:39]
	v_mfma_f32_16x16x32_bf16 v[4:7], v[132:135], v[218:221], v[4:7]
	v_mfma_f32_16x16x32_bf16 v[4:7], v[128:131], v[210:213], v[4:7]
	v_mfma_f32_16x16x32_bf16 v[0:3], v[136:139], v[210:213], v[0:3]
	v_mfma_f32_16x16x32_bf16 v[0:3], v[140:143], v[218:221], v[0:3]
	v_mfma_f32_16x16x32_bf16 v[48:51], v[140:143], v[180:183], v[48:51]
	v_mfma_f32_16x16x32_bf16 v[48:51], v[136:139], v[160:163], v[48:51]
	v_mfma_f32_16x16x32_bf16 v[32:35], v[136:139], v[164:167], v[32:35]
	v_mfma_f32_16x16x32_bf16 v[32:35], v[140:143], v[202:205], v[32:35]
	v_mfma_f32_16x16x32_bf16 v[8:11], v[140:143], v[214:217], v[8:11]
	v_mfma_f32_16x16x32_bf16 v[8:11], v[136:139], v[206:209], v[8:11]
	s_setprio 0
	s_setprio 3
	v_mfma_f32_16x16x32_bf16 v[28:31], v[144:147], v[206:209], v[28:31]
	v_mfma_f32_16x16x32_bf16 v[28:31], v[148:151], v[214:217], v[28:31]
	v_mfma_f32_16x16x32_bf16 v[64:67], v[148:151], v[180:183], v[64:67]
	v_mfma_f32_16x16x32_bf16 v[64:67], v[144:147], v[160:163], v[64:67]
	v_mfma_f32_16x16x32_bf16 v[44:47], v[144:147], v[164:167], v[44:47]
	v_mfma_f32_16x16x32_bf16 v[44:47], v[148:151], v[202:205], v[44:47]
	v_mfma_f32_16x16x32_bf16 v[16:19], v[148:151], v[218:221], v[16:19]
	v_mfma_f32_16x16x32_bf16 v[16:19], v[144:147], v[210:213], v[16:19]
	v_mfma_f32_16x16x32_bf16 v[12:15], v[152:155], v[210:213], v[12:15]
	v_mfma_f32_16x16x32_bf16 v[12:15], v[156:159], v[218:221], v[12:15]
	v_mfma_f32_16x16x32_bf16 v[56:59], v[156:159], v[180:183], v[56:59]
	v_mfma_f32_16x16x32_bf16 v[56:59], v[152:155], v[160:163], v[56:59]
	v_mfma_f32_16x16x32_bf16 v[40:43], v[152:155], v[164:167], v[40:43]
	v_mfma_f32_16x16x32_bf16 v[40:43], v[156:159], v[202:205], v[40:43]
	v_mfma_f32_16x16x32_bf16 v[24:27], v[156:159], v[214:217], v[24:27]
	v_mfma_f32_16x16x32_bf16 v[24:27], v[152:155], v[206:209], v[24:27]
	s_setprio 0
	s_barrier
	s_add_i32 s56, s56, 2
	s_add_u32 s22, s22, 0x100
	s_addc_u32 s23, s23, 0
	s_add_u32 s54, s54, 0x100
	s_addc_u32 s55, s55, 0
	s_cmpk_gt_u32 s56, 0xa9
	s_cbranch_scc0 .LBB0_1096
	s_and_b64 vcc, exec, s[8:9]
	s_cbranch_vccz .LBB0_1099
	s_barrier
